# bf16 weight transposes for layer 1 and for layer 0 ff1/ff2 moved out of the prologue into the idle CUs of the w_in / ff1 tail rounds
# speedup vs baseline: 1.0526x; 1.0125x over previous
; #define KIN(i) ((const float*)kptr<float>(i))
; __global__ void __launch_bounds__(NWAVES * 64, 2) fwd_mega(Args args) {
;     ...
;         for (int it = gw; it < 2 * I_L + I_CV; it += NGW) {
;             if (it < 2 * I_L) {
;                 const int l = it / I_L; int r = it % I_L; unsigned char* wl = ws + WS_W + (size_t)l * W_LAYER;
;                 if (r < I_IN) { const int kb = r / 40, nb = r % 40; transpose_item(KIN(6) + (size_t)l * DM * INC, INC, (bf16_t*)(wl + W_IN), DM, KIN(5) + l * DM, 64 * kb, 64 * nb, win_dst(64 * nb + (lane & 32)) + (lane & 31), lane); continue; } r -= I_IN;
.LBB0_20:
	v_mov_b32_e32 v74, v173
	s_load_dwordx2 s[10:11], s[0:1], 0x98
	v_readfirstlane_b32 s2, v74
	s_ashr_i32 s26, s2, 6
	s_lshl_b32 s2, s76, 3
	s_add_i32 s26, s26, s2
	s_mov_b64 s[96:97], s[80:81]
	s_mov_b32 s94, s76
	s_mov_b32 s95, s2
	s_cmpk_gt_i32 s26, 0x37f
	v_and_b32_e32 v0, 63, v74
	s_cbranch_scc1 .LBB0_43
	v_mov_b32_e32 v3, 0
	v_and_b32_e32 v1, 32, v74
	v_and_b32_e32 v75, 31, v74
	s_lshl_b32 s27, s26, 6
	s_lshl_b32 s28, s82, 6
	s_lshl_b32 s29, s26, 2
	s_lshl_b32 s30, s82, 2
	s_movk_i32 s31, 0x2000
	s_movk_i32 s34, 0x4000
	s_movk_i32 s35, 0x6000
	s_mov_b32 s36, 0x8000
	s_mov_b32 s37, 0xa000
	s_mov_b32 s38, 0xc000
	s_mov_b32 s39, 0xe000
	s_mov_b32 s40, 0x10000
	s_mov_b32 s41, 0x12000
	s_mov_b32 s42, 0x14000
	s_mov_b32 s43, 0x16000
	s_mov_b32 s44, 0x18000
	s_mov_b32 s45, 0x1a000
	s_mov_b32 s46, 0x1c000
	s_mov_b32 s47, 0x1e000
	s_mov_b32 s48, 0x20000
	s_mov_b32 s50, 0x22000
	s_mov_b32 s51, 0x24000
	s_mov_b32 s52, 0x26000
	s_mov_b32 s53, 0x28000
	s_mov_b32 s54, 0x2a000
	s_mov_b32 s55, 0x2c000
	s_mov_b32 s56, 0x2e000
	s_mov_b32 s57, 0x30000
	s_mov_b32 s58, 0x32000
	s_mov_b32 s59, 0x34000
	s_mov_b32 s60, 0x36000
	s_mov_b32 s61, 0x38000
	s_mov_b32 s62, 0x3a000
	s_mov_b32 s63, 0x3c000
	s_mov_b32 s64, 0x3e000
	s_mov_b32 s65, 0x3f000
	s_mov_b32 s66, 0x48000
	s_mov_b32 s67, 0x50000
	s_mov_b32 s68, 0x5c000
	s_mov_b32 s69, 0x64000
	s_mov_b32 s70, 0x70000
	s_mov_b32 s71, 0x78000
	s_mov_b32 s72, 0x84000
	s_mov_b32 s73, 0x8c000
	s_mov_b32 s74, 0x98000
	v_lshlrev_b32_e32 v2, 2, v0
	s_mov_b32 s75, 0x6e000
	s_mov_b32 s76, 0x73000
	s_mov_b32 s77, 0x75000
	s_mov_b32 s78, 0x7a000
	s_mov_b32 s79, 0x7d000
	s_mov_b32 s80, 0x7f000
	s_mov_b32 s81, 0x82000
	s_mov_b32 s83, 0x87000
	s_mov_b32 s4, 0x89000
	s_mov_b32 s84, 0x8e000
	s_mov_b32 s85, 0x91000
	s_mov_b32 s86, 0x93000
	s_mov_b32 s87, 0x96000
	s_mov_b32 s88, 0x9b000
	s_mov_b32 s89, 0x9d000
	s_mov_b32 s90, s26
	s_mov_b32 s3, 0
	s_mov_b64 s[12:13], 0xa00000
	s_branch .LBB0_24

; __device__ __forceinline__ unsigned pk2(float lo, float hi) { f32x2 v = {lo, hi}; bf16x2_t b = __builtin_convertvector(v, bf16x2_t); return __builtin_bit_cast(unsigned, b); }
; __device__ __forceinline__ void transpose_item(const float* __restrict__ W, int ldw, bf16_t* __restrict__ WT, int ldo, const float* __restrict__ g, int k0, int n0, int dstrow, int lane) {
;     ...
;     for (int c = 0; c < 8; ++c) { u32x4 o; o.x = pk2(v[8 * c], v[8 * c + 1]); o.y = pk2(v[8 * c + 2], v[8 * c + 3]); o.z = pk2(v[8 * c + 4], v[8 * c + 5]); o.w = pk2(v[8 * c + 6], v[8 * c + 7]);
;         *(u32x4*)(dst + 8 * c) = o; }
.LBB0_23:
	s_waitcnt vmcnt(53)
	v_cvt_pk_bf16_f32 v61, v4, v5
	s_waitcnt vmcnt(51)
	v_cvt_pk_bf16_f32 v62, v6, v7
	s_waitcnt vmcnt(47)
	v_cvt_pk_bf16_f32 v4, v24, v25
	s_waitcnt vmcnt(45)
	v_cvt_pk_bf16_f32 v5, v10, v11
	s_waitcnt vmcnt(43)
	v_cvt_pk_bf16_f32 v6, v12, v13
	s_waitcnt vmcnt(41)
	v_cvt_pk_bf16_f32 v7, v14, v15
	global_store_dwordx4 v[66:67], v[4:7], off offset:32
	s_add_i32 s90, s90, s82
	s_add_i32 s27, s27, s28
	s_waitcnt vmcnt(40)
	v_cvt_pk_bf16_f32 v4, v32, v33
	s_waitcnt vmcnt(38)
	v_cvt_pk_bf16_f32 v5, v16, v17
	s_waitcnt vmcnt(36)
	v_cvt_pk_bf16_f32 v6, v18, v19
	s_waitcnt vmcnt(34)
	v_cvt_pk_bf16_f32 v7, v20, v21
	global_store_dwordx4 v[66:67], v[4:7], off offset:48
	s_add_i32 s29, s29, s30
	v_cvt_pk_bf16_f32 v60, v22, v23
	s_waitcnt vmcnt(33)
	v_cvt_pk_bf16_f32 v4, v34, v35
	s_waitcnt vmcnt(31)
	v_cvt_pk_bf16_f32 v5, v26, v27
	s_waitcnt vmcnt(29)
	v_cvt_pk_bf16_f32 v6, v28, v29
	s_waitcnt vmcnt(27)
	v_cvt_pk_bf16_f32 v7, v30, v31
	global_store_dwordx4 v[66:67], v[4:7], off offset:64
	v_cvt_pk_bf16_f32 v63, v8, v9
	s_cmpk_gt_i32 s90, 0x37f
	s_waitcnt vmcnt(26)
	v_cvt_pk_bf16_f32 v4, v42, v43
	s_waitcnt vmcnt(24)
	v_cvt_pk_bf16_f32 v5, v36, v37
	s_waitcnt vmcnt(22)
	v_cvt_pk_bf16_f32 v6, v38, v39
	s_waitcnt vmcnt(20)
	v_cvt_pk_bf16_f32 v7, v40, v41
	global_store_dwordx4 v[66:67], v[4:7], off offset:80
	global_store_dwordx4 v[66:67], v[60:63], off offset:16
	s_waitcnt vmcnt(20)
	v_cvt_pk_bf16_f32 v4, v50, v51
	s_waitcnt vmcnt(18)
	v_cvt_pk_bf16_f32 v5, v44, v45
	s_waitcnt vmcnt(16)
	v_cvt_pk_bf16_f32 v6, v46, v47
	s_waitcnt vmcnt(14)
	v_cvt_pk_bf16_f32 v7, v48, v49
	global_store_dwordx4 v[66:67], v[4:7], off offset:96
	s_waitcnt vmcnt(13)
	s_nop 0
	v_cvt_pk_bf16_f32 v4, v52, v53
	s_waitcnt vmcnt(11)
	v_cvt_pk_bf16_f32 v5, v54, v55
	s_waitcnt vmcnt(9)
	v_cvt_pk_bf16_f32 v6, v56, v57
	s_waitcnt vmcnt(7)
	v_cvt_pk_bf16_f32 v7, v58, v59
	global_store_dwordx4 v[66:67], v[4:7], off offset:112
	s_cbranch_scc1 .LBB0_43

; #define KIN(i) ((const float*)kptr<float>(i))
; __device__ __forceinline__ void transpose_item(const float* __restrict__ W, int ldw, bf16_t* __restrict__ WT, int ldo, const float* __restrict__ g, int k0, int n0, int dstrow, int lane) {
;     const float* src = W + (size_t)k0 * ldw + n0 + lane;
;     float v[64];
; #pragma unroll
;     for (int i = 0; i < 64; ++i) v[i] = __builtin_nontemporal_load(src + (size_t)i * ldw);
; __global__ void __launch_bounds__(NWAVES * 64, 2) fwd_mega(Args args) {
;     ...
;                 if (r < I_F1) { const int kb = r / 64, nb = r % 64; transpose_item(KIN(16) + (size_t)l * DM * DFF, DFF, (bf16_t*)(wl + W_FF1), DM, KIN(15) + l * DM, 64 * kb, 64 * nb, 64 * nb + lane, lane); continue; } r -= I_F1;
.LBB0_351:
	s_cmp_lg_u32 s62, 0
	s_cbranch_scc1 .Llt0_done
	v_readfirstlane_b32 s4, v173
	s_nop 3
	s_lshr_b32 s4, s4, 6
	s_lshl_b32 s63, s76, 3
	s_add_u32 s63, s63, s4
	s_lshl_b32 s68, s33, 3
	s_cmp_gt_u32 s33, 0x9c
	s_cbranch_scc0 .Llt0_loop0
	s_cmp_lt_u32 s76, 156
	s_cbranch_scc1 .Llt0_done
	s_sub_u32 s63, s63, 0x4e0
	s_sub_u32 s68, s68, 0x4e0
.Llt0_loop0:
	s_add_u32 s63, s63, 0x380
.Llt0_loop:
	s_cmpk_lt_u32 s63, 0xb80
	s_cbranch_scc0 .Llt0_done
	s_mov_b32 s4, s63
	s_cmpk_lt_u32 s63, 0x780
	s_cbranch_scc0 .Llt0_n0
	s_sub_u32 s4, s63, 0x380
	s_lshr_b32 s2, s4, 6
	s_and_b32 s3, s4, 63
	s_load_dwordx2 s[64:65], s[0:1], 0x80
	s_load_dwordx2 s[66:67], s[0:1], 0x98
	v_lshl_add_u32 v142, s3, 6, v191
	v_lshlrev_b32_e32 v143, 11, v142
	s_lshl_b32 s4, s2, 7
	v_add_u32_e32 v143, s4, v143
	v_lshlrev_b32_e32 v141, 2, v191
	s_waitcnt lgkmcnt(0)
	s_add_u32 s66, s66, 0xa00000
	s_addc_u32 s67, s67, 0
	s_mul_i32 s4, s2, 0x100000
	s_add_u32 s4, s4, 0x0
	s_add_u32 s64, s64, s4
	s_addc_u32 s65, s65, 0
	s_lshl_b32 s4, s3, 8
	s_add_u32 s64, s64, s4
	s_addc_u32 s65, s65, 0
	s_lshl_b32 s4, s2, 8
	s_load_dwordx2 s[2:3], s[0:1], 0x78
	global_load_dword v0, v141, s[64:65] nt
	s_add_u32 s64, s64, 0x4000
	s_addc_u32 s65, s65, 0
	global_load_dword v1, v141, s[64:65] nt
	s_add_u32 s64, s64, 0x4000
	s_addc_u32 s65, s65, 0
	global_load_dword v2, v141, s[64:65] nt
	s_add_u32 s64, s64, 0x4000
	s_addc_u32 s65, s65, 0
	global_load_dword v3, v141, s[64:65] nt
	s_add_u32 s64, s64, 0x4000
	s_addc_u32 s65, s65, 0
	global_load_dword v4, v141, s[64:65] nt
	s_add_u32 s64, s64, 0x4000
	s_addc_u32 s65, s65, 0
	global_load_dword v5, v141, s[64:65] nt
	s_add_u32 s64, s64, 0x4000
	s_addc_u32 s65, s65, 0
	global_load_dword v6, v141, s[64:65] nt
	s_add_u32 s64, s64, 0x4000
	s_addc_u32 s65, s65, 0
	global_load_dword v7, v141, s[64:65] nt
	s_add_u32 s64, s64, 0x4000
	s_addc_u32 s65, s65, 0
	global_load_dword v8, v141, s[64:65] nt
	s_add_u32 s64, s64, 0x4000
	s_addc_u32 s65, s65, 0
	global_load_dword v9, v141, s[64:65] nt
	s_add_u32 s64, s64, 0x4000
	s_addc_u32 s65, s65, 0
	global_load_dword v10, v141, s[64:65] nt
	s_add_u32 s64, s64, 0x4000
	s_addc_u32 s65, s65, 0
	global_load_dword v11, v141, s[64:65] nt
	s_add_u32 s64, s64, 0x4000
	s_addc_u32 s65, s65, 0
	global_load_dword v12, v141, s[64:65] nt
	s_add_u32 s64, s64, 0x4000
	s_addc_u32 s65, s65, 0
	global_load_dword v13, v141, s[64:65] nt
	s_add_u32 s64, s64, 0x4000
	s_addc_u32 s65, s65, 0
	global_load_dword v14, v141, s[64:65] nt
	s_add_u32 s64, s64, 0x4000
	s_addc_u32 s65, s65, 0
	global_load_dword v15, v141, s[64:65] nt
	s_add_u32 s64, s64, 0x4000
	s_addc_u32 s65, s65, 0
	global_load_dword v16, v141, s[64:65] nt
	s_add_u32 s64, s64, 0x4000
	s_addc_u32 s65, s65, 0
	global_load_dword v17, v141, s[64:65] nt
	s_add_u32 s64, s64, 0x4000
	s_addc_u32 s65, s65, 0
	global_load_dword v18, v141, s[64:65] nt
	s_add_u32 s64, s64, 0x4000
	s_addc_u32 s65, s65, 0
	global_load_dword v19, v141, s[64:65] nt
	s_add_u32 s64, s64, 0x4000
	s_addc_u32 s65, s65, 0
	global_load_dword v20, v141, s[64:65] nt
	s_add_u32 s64, s64, 0x4000
	s_addc_u32 s65, s65, 0
	global_load_dword v21, v141, s[64:65] nt
	s_add_u32 s64, s64, 0x4000
	s_addc_u32 s65, s65, 0
	global_load_dword v22, v141, s[64:65] nt
	s_add_u32 s64, s64, 0x4000
	s_addc_u32 s65, s65, 0
	global_load_dword v23, v141, s[64:65] nt
	s_add_u32 s64, s64, 0x4000
	s_addc_u32 s65, s65, 0
	global_load_dword v24, v141, s[64:65] nt
	s_add_u32 s64, s64, 0x4000
	s_addc_u32 s65, s65, 0
	global_load_dword v25, v141, s[64:65] nt
	s_add_u32 s64, s64, 0x4000
	s_addc_u32 s65, s65, 0
	global_load_dword v26, v141, s[64:65] nt
	s_add_u32 s64, s64, 0x4000
	s_addc_u32 s65, s65, 0
	global_load_dword v27, v141, s[64:65] nt
	s_add_u32 s64, s64, 0x4000
	s_addc_u32 s65, s65, 0
	global_load_dword v28, v141, s[64:65] nt
	s_add_u32 s64, s64, 0x4000
	s_addc_u32 s65, s65, 0
	global_load_dword v29, v141, s[64:65] nt
	s_add_u32 s64, s64, 0x4000
	s_addc_u32 s65, s65, 0
	global_load_dword v30, v141, s[64:65] nt
	s_add_u32 s64, s64, 0x4000
	s_addc_u32 s65, s65, 0
	global_load_dword v31, v141, s[64:65] nt
	s_add_u32 s64, s64, 0x4000
	s_addc_u32 s65, s65, 0
	global_load_dword v32, v141, s[64:65] nt
	s_add_u32 s64, s64, 0x4000
	s_addc_u32 s65, s65, 0
	global_load_dword v33, v141, s[64:65] nt
	s_add_u32 s64, s64, 0x4000
	s_addc_u32 s65, s65, 0
	global_load_dword v34, v141, s[64:65] nt
	s_add_u32 s64, s64, 0x4000
	s_addc_u32 s65, s65, 0
	global_load_dword v35, v141, s[64:65] nt
	s_add_u32 s64, s64, 0x4000
	s_addc_u32 s65, s65, 0
	global_load_dword v36, v141, s[64:65] nt
	s_add_u32 s64, s64, 0x4000
	s_addc_u32 s65, s65, 0
	global_load_dword v37, v141, s[64:65] nt
	s_add_u32 s64, s64, 0x4000
	s_addc_u32 s65, s65, 0
	global_load_dword v38, v141, s[64:65] nt
	s_add_u32 s64, s64, 0x4000
	s_addc_u32 s65, s65, 0
	global_load_dword v39, v141, s[64:65] nt
	s_add_u32 s64, s64, 0x4000
	s_addc_u32 s65, s65, 0
	global_load_dword v40, v141, s[64:65] nt
	s_add_u32 s64, s64, 0x4000
	s_addc_u32 s65, s65, 0
	global_load_dword v41, v141, s[64:65] nt
	s_add_u32 s64, s64, 0x4000
	s_addc_u32 s65, s65, 0
	global_load_dword v42, v141, s[64:65] nt
	s_add_u32 s64, s64, 0x4000
	s_addc_u32 s65, s65, 0
	global_load_dword v43, v141, s[64:65] nt
	s_add_u32 s64, s64, 0x4000
	s_addc_u32 s65, s65, 0
	global_load_dword v44, v141, s[64:65] nt
	s_add_u32 s64, s64, 0x4000
	s_addc_u32 s65, s65, 0
	global_load_dword v45, v141, s[64:65] nt
	s_add_u32 s64, s64, 0x4000
	s_addc_u32 s65, s65, 0
	global_load_dword v46, v141, s[64:65] nt
	s_add_u32 s64, s64, 0x4000
	s_addc_u32 s65, s65, 0
	global_load_dword v47, v141, s[64:65] nt
	s_add_u32 s64, s64, 0x4000
	s_addc_u32 s65, s65, 0
; __device__ __forceinline__ void transpose_item(const float* __restrict__ W, int ldw, bf16_t* __restrict__ WT, int ldo, const float* __restrict__ g, int k0, int n0, int dstrow, int lane) {
;     ...
;     for (int i = 0; i < 64; ++i) v[i] = __builtin_nontemporal_load(src + (size_t)i * ldw);
;     if (g) {
; #pragma unroll
;         for (int i = 0; i < 64; ++i) v[i] *= g[k0 + i];
	global_load_dword v48, v141, s[64:65] nt
	s_add_u32 s64, s64, 0x4000
	s_addc_u32 s65, s65, 0
	global_load_dword v49, v141, s[64:65] nt
	s_add_u32 s64, s64, 0x4000
	s_addc_u32 s65, s65, 0
	global_load_dword v50, v141, s[64:65] nt
	s_add_u32 s64, s64, 0x4000
	s_addc_u32 s65, s65, 0
	global_load_dword v51, v141, s[64:65] nt
	s_add_u32 s64, s64, 0x4000
	s_addc_u32 s65, s65, 0
	global_load_dword v52, v141, s[64:65] nt
	s_add_u32 s64, s64, 0x4000
	s_addc_u32 s65, s65, 0
	global_load_dword v53, v141, s[64:65] nt
	s_add_u32 s64, s64, 0x4000
	s_addc_u32 s65, s65, 0
	global_load_dword v54, v141, s[64:65] nt
	s_add_u32 s64, s64, 0x4000
	s_addc_u32 s65, s65, 0
	global_load_dword v55, v141, s[64:65] nt
	s_add_u32 s64, s64, 0x4000
	s_addc_u32 s65, s65, 0
	global_load_dword v56, v141, s[64:65] nt
	s_add_u32 s64, s64, 0x4000
	s_addc_u32 s65, s65, 0
	global_load_dword v57, v141, s[64:65] nt
	s_add_u32 s64, s64, 0x4000
	s_addc_u32 s65, s65, 0
	global_load_dword v58, v141, s[64:65] nt
	s_add_u32 s64, s64, 0x4000
	s_addc_u32 s65, s65, 0
	global_load_dword v59, v141, s[64:65] nt
	s_add_u32 s64, s64, 0x4000
	s_addc_u32 s65, s65, 0
	global_load_dword v60, v141, s[64:65] nt
	s_add_u32 s64, s64, 0x4000
	s_addc_u32 s65, s65, 0
	global_load_dword v61, v141, s[64:65] nt
	s_add_u32 s64, s64, 0x4000
	s_addc_u32 s65, s65, 0
	global_load_dword v62, v141, s[64:65] nt
	s_add_u32 s64, s64, 0x4000
	s_addc_u32 s65, s65, 0
	global_load_dword v63, v141, s[64:65] nt
	s_waitcnt lgkmcnt(0)
	s_add_u32 s4, s4, 0x0
	s_add_u32 s2, s2, s4
	s_addc_u32 s3, s3, 0
	global_load_dword v64, v153, s[2:3]
	global_load_dword v65, v153, s[2:3] offset:4
	global_load_dword v66, v153, s[2:3] offset:8
	global_load_dword v67, v153, s[2:3] offset:12
	global_load_dword v68, v153, s[2:3] offset:16
	global_load_dword v69, v153, s[2:3] offset:20
	global_load_dword v70, v153, s[2:3] offset:24
	global_load_dword v71, v153, s[2:3] offset:28
	global_load_dword v72, v153, s[2:3] offset:32
	global_load_dword v73, v153, s[2:3] offset:36
	global_load_dword v74, v153, s[2:3] offset:40
	global_load_dword v75, v153, s[2:3] offset:44
	global_load_dword v76, v153, s[2:3] offset:48
	global_load_dword v77, v153, s[2:3] offset:52
	global_load_dword v78, v153, s[2:3] offset:56
	global_load_dword v79, v153, s[2:3] offset:60
	global_load_dword v80, v153, s[2:3] offset:64
	global_load_dword v81, v153, s[2:3] offset:68
	global_load_dword v82, v153, s[2:3] offset:72
	global_load_dword v83, v153, s[2:3] offset:76
	global_load_dword v84, v153, s[2:3] offset:80
	global_load_dword v85, v153, s[2:3] offset:84
	global_load_dword v86, v153, s[2:3] offset:88
	global_load_dword v87, v153, s[2:3] offset:92
	global_load_dword v88, v153, s[2:3] offset:96
	global_load_dword v89, v153, s[2:3] offset:100
	global_load_dword v90, v153, s[2:3] offset:104
	global_load_dword v91, v153, s[2:3] offset:108
	global_load_dword v92, v153, s[2:3] offset:112
	global_load_dword v93, v153, s[2:3] offset:116
	global_load_dword v94, v153, s[2:3] offset:120
	global_load_dword v95, v153, s[2:3] offset:124
	global_load_dword v96, v153, s[2:3] offset:128
	global_load_dword v97, v153, s[2:3] offset:132
	global_load_dword v98, v153, s[2:3] offset:136
	global_load_dword v99, v153, s[2:3] offset:140
	global_load_dword v100, v153, s[2:3] offset:144
	global_load_dword v101, v153, s[2:3] offset:148
	global_load_dword v102, v153, s[2:3] offset:152
	global_load_dword v103, v153, s[2:3] offset:156
	global_load_dword v104, v153, s[2:3] offset:160
	global_load_dword v105, v153, s[2:3] offset:164
	global_load_dword v106, v153, s[2:3] offset:168
	global_load_dword v107, v153, s[2:3] offset:172
	global_load_dword v108, v153, s[2:3] offset:176
	global_load_dword v109, v153, s[2:3] offset:180
	global_load_dword v110, v153, s[2:3] offset:184
	global_load_dword v111, v153, s[2:3] offset:188
	global_load_dword v112, v153, s[2:3] offset:192
	global_load_dword v113, v153, s[2:3] offset:196
	global_load_dword v114, v153, s[2:3] offset:200
	global_load_dword v115, v153, s[2:3] offset:204
	global_load_dword v116, v153, s[2:3] offset:208
	global_load_dword v117, v153, s[2:3] offset:212
	global_load_dword v118, v153, s[2:3] offset:216
	global_load_dword v119, v153, s[2:3] offset:220
	global_load_dword v120, v153, s[2:3] offset:224
	global_load_dword v121, v153, s[2:3] offset:228
	global_load_dword v122, v153, s[2:3] offset:232
	global_load_dword v123, v153, s[2:3] offset:236
	global_load_dword v124, v153, s[2:3] offset:240
	global_load_dword v125, v153, s[2:3] offset:244
	global_load_dword v126, v153, s[2:3] offset:248
	global_load_dword v127, v153, s[2:3] offset:252
	s_waitcnt vmcnt(0)
; __device__ __forceinline__ unsigned pk2(float lo, float hi) { f32x2 v = {lo, hi}; bf16x2_t b = __builtin_convertvector(v, bf16x2_t); return __builtin_bit_cast(unsigned, b); }
; #define KIN(i) ((const float*)kptr<float>(i))
; __device__ __forceinline__ void transpose_item(const float* __restrict__ W, int ldw, bf16_t* __restrict__ WT, int ldo, const float* __restrict__ g, int k0, int n0, int dstrow, int lane) {
;     ...
;         for (int i = 0; i < 64; ++i) v[i] *= g[k0 + i];
;     }
;     bf16_t* dst = WT + (size_t)dstrow * ldo + k0;
; #pragma unroll
;     for (int c = 0; c < 8; ++c) { u32x4 o; o.x = pk2(v[8 * c], v[8 * c + 1]); o.y = pk2(v[8 * c + 2], v[8 * c + 3]); o.z = pk2(v[8 * c + 4], v[8 * c + 5]); o.w = pk2(v[8 * c + 6], v[8 * c + 7]);
;         *(u32x4*)(dst + 8 * c) = o; }
; __global__ void __launch_bounds__(NWAVES * 64, 2) fwd_mega(Args args) {
;     ...
;                 { const int kb = r / 16, nb = r % 16; transpose_item(KIN(17) + (size_t)l * DFF * DM, DM, (bf16_t*)(wl + W_FF2), DFF, nullptr, 64 * kb, 64 * nb, 64 * nb + lane, lane); }
	v_mul_f32_e32 v0, v0, v64
	v_mul_f32_e32 v1, v1, v65
	v_mul_f32_e32 v2, v2, v66
	v_mul_f32_e32 v3, v3, v67
	v_mul_f32_e32 v4, v4, v68
	v_mul_f32_e32 v5, v5, v69
	v_mul_f32_e32 v6, v6, v70
	v_mul_f32_e32 v7, v7, v71
	v_mul_f32_e32 v8, v8, v72
	v_mul_f32_e32 v9, v9, v73
	v_mul_f32_e32 v10, v10, v74
	v_mul_f32_e32 v11, v11, v75
	v_mul_f32_e32 v12, v12, v76
	v_mul_f32_e32 v13, v13, v77
	v_mul_f32_e32 v14, v14, v78
	v_mul_f32_e32 v15, v15, v79
	v_mul_f32_e32 v16, v16, v80
	v_mul_f32_e32 v17, v17, v81
	v_mul_f32_e32 v18, v18, v82
	v_mul_f32_e32 v19, v19, v83
	v_mul_f32_e32 v20, v20, v84
	v_mul_f32_e32 v21, v21, v85
	v_mul_f32_e32 v22, v22, v86
	v_mul_f32_e32 v23, v23, v87
	v_mul_f32_e32 v24, v24, v88
	v_mul_f32_e32 v25, v25, v89
	v_mul_f32_e32 v26, v26, v90
	v_mul_f32_e32 v27, v27, v91
	v_mul_f32_e32 v28, v28, v92
	v_mul_f32_e32 v29, v29, v93
	v_mul_f32_e32 v30, v30, v94
	v_mul_f32_e32 v31, v31, v95
	v_mul_f32_e32 v32, v32, v96
	v_mul_f32_e32 v33, v33, v97
	v_mul_f32_e32 v34, v34, v98
	v_mul_f32_e32 v35, v35, v99
	v_mul_f32_e32 v36, v36, v100
	v_mul_f32_e32 v37, v37, v101
	v_mul_f32_e32 v38, v38, v102
	v_mul_f32_e32 v39, v39, v103
	v_mul_f32_e32 v40, v40, v104
	v_mul_f32_e32 v41, v41, v105
	v_mul_f32_e32 v42, v42, v106
	v_mul_f32_e32 v43, v43, v107
	v_mul_f32_e32 v44, v44, v108
	v_mul_f32_e32 v45, v45, v109
	v_mul_f32_e32 v46, v46, v110
	v_mul_f32_e32 v47, v47, v111
	v_mul_f32_e32 v48, v48, v112
	v_mul_f32_e32 v49, v49, v113
	v_mul_f32_e32 v50, v50, v114
	v_mul_f32_e32 v51, v51, v115
	v_mul_f32_e32 v52, v52, v116
	v_mul_f32_e32 v53, v53, v117
	v_mul_f32_e32 v54, v54, v118
	v_mul_f32_e32 v55, v55, v119
	v_mul_f32_e32 v56, v56, v120
	v_mul_f32_e32 v57, v57, v121
	v_mul_f32_e32 v58, v58, v122
	v_mul_f32_e32 v59, v59, v123
	v_mul_f32_e32 v60, v60, v124
	v_mul_f32_e32 v61, v61, v125
	v_mul_f32_e32 v62, v62, v126
	v_mul_f32_e32 v63, v63, v127
	v_cvt_pk_bf16_f32 v0, v0, v1
	v_cvt_pk_bf16_f32 v1, v2, v3
	v_cvt_pk_bf16_f32 v2, v4, v5
	v_cvt_pk_bf16_f32 v3, v6, v7
	v_cvt_pk_bf16_f32 v4, v8, v9
	v_cvt_pk_bf16_f32 v5, v10, v11
	v_cvt_pk_bf16_f32 v6, v12, v13
	v_cvt_pk_bf16_f32 v7, v14, v15
	v_cvt_pk_bf16_f32 v8, v16, v17
	v_cvt_pk_bf16_f32 v9, v18, v19
	v_cvt_pk_bf16_f32 v10, v20, v21
	v_cvt_pk_bf16_f32 v11, v22, v23
	v_cvt_pk_bf16_f32 v12, v24, v25
	v_cvt_pk_bf16_f32 v13, v26, v27
	v_cvt_pk_bf16_f32 v14, v28, v29
	v_cvt_pk_bf16_f32 v15, v30, v31
	v_cvt_pk_bf16_f32 v16, v32, v33
	v_cvt_pk_bf16_f32 v17, v34, v35
	v_cvt_pk_bf16_f32 v18, v36, v37
	v_cvt_pk_bf16_f32 v19, v38, v39
	v_cvt_pk_bf16_f32 v20, v40, v41
	v_cvt_pk_bf16_f32 v21, v42, v43
	v_cvt_pk_bf16_f32 v22, v44, v45
	v_cvt_pk_bf16_f32 v23, v46, v47
	v_cvt_pk_bf16_f32 v24, v48, v49
	v_cvt_pk_bf16_f32 v25, v50, v51
	v_cvt_pk_bf16_f32 v26, v52, v53
	v_cvt_pk_bf16_f32 v27, v54, v55
	v_cvt_pk_bf16_f32 v28, v56, v57
	v_cvt_pk_bf16_f32 v29, v58, v59
	v_cvt_pk_bf16_f32 v30, v60, v61
	v_cvt_pk_bf16_f32 v31, v62, v63
	global_store_dwordx4 v143, v[0:3], s[66:67]
	global_store_dwordx4 v143, v[4:7], s[66:67] offset:16
	global_store_dwordx4 v143, v[8:11], s[66:67] offset:32
	global_store_dwordx4 v143, v[12:15], s[66:67] offset:48
	global_store_dwordx4 v143, v[16:19], s[66:67] offset:64
	global_store_dwordx4 v143, v[20:23], s[66:67] offset:80
	global_store_dwordx4 v143, v[24:27], s[66:67] offset:96
	global_store_dwordx4 v143, v[28:31], s[66:67] offset:112
	s_branch .Llt0_next
.Llt0_n0:
	s_sub_u32 s4, s63, 0x780
	s_lshr_b32 s2, s4, 4
	s_and_b32 s3, s4, 15
	s_load_dwordx2 s[64:65], s[0:1], 0x88
	s_load_dwordx2 s[66:67], s[0:1], 0x98
	v_lshl_add_u32 v142, s3, 6, v191
	v_lshlrev_b32_e32 v143, 13, v142
	s_lshl_b32 s4, s2, 7
	v_add_u32_e32 v143, s4, v143
	v_lshlrev_b32_e32 v141, 2, v191
	s_waitcnt lgkmcnt(0)
	s_add_u32 s66, s66, 0x1200000
	s_addc_u32 s67, s67, 0
	s_mul_i32 s4, s2, 0x40000
	s_add_u32 s4, s4, 0x0
	s_add_u32 s64, s64, s4
	s_addc_u32 s65, s65, 0
	s_lshl_b32 s4, s3, 8
	s_add_u32 s64, s64, s4
	s_addc_u32 s65, s65, 0
	global_load_dword v0, v141, s[64:65] nt
	s_add_u32 s64, s64, 0x1000
	s_addc_u32 s65, s65, 0
	global_load_dword v1, v141, s[64:65] nt
	s_add_u32 s64, s64, 0x1000
	s_addc_u32 s65, s65, 0
	global_load_dword v2, v141, s[64:65] nt
	s_add_u32 s64, s64, 0x1000
	s_addc_u32 s65, s65, 0
	global_load_dword v3, v141, s[64:65] nt
	s_add_u32 s64, s64, 0x1000
	s_addc_u32 s65, s65, 0
	global_load_dword v4, v141, s[64:65] nt
	s_add_u32 s64, s64, 0x1000
	s_addc_u32 s65, s65, 0
	global_load_dword v5, v141, s[64:65] nt
	s_add_u32 s64, s64, 0x1000
	s_addc_u32 s65, s65, 0
	global_load_dword v6, v141, s[64:65] nt
	s_add_u32 s64, s64, 0x1000
	s_addc_u32 s65, s65, 0
	global_load_dword v7, v141, s[64:65] nt
	s_add_u32 s64, s64, 0x1000
	s_addc_u32 s65, s65, 0
	global_load_dword v8, v141, s[64:65] nt
	s_add_u32 s64, s64, 0x1000
	s_addc_u32 s65, s65, 0
	global_load_dword v9, v141, s[64:65] nt
	s_add_u32 s64, s64, 0x1000
	s_addc_u32 s65, s65, 0
	global_load_dword v10, v141, s[64:65] nt
	s_add_u32 s64, s64, 0x1000
	s_addc_u32 s65, s65, 0
	global_load_dword v11, v141, s[64:65] nt
	s_add_u32 s64, s64, 0x1000
	s_addc_u32 s65, s65, 0
	global_load_dword v12, v141, s[64:65] nt
	s_add_u32 s64, s64, 0x1000
	s_addc_u32 s65, s65, 0
	global_load_dword v13, v141, s[64:65] nt
	s_add_u32 s64, s64, 0x1000
	s_addc_u32 s65, s65, 0
	global_load_dword v14, v141, s[64:65] nt
	s_add_u32 s64, s64, 0x1000
	s_addc_u32 s65, s65, 0
	global_load_dword v15, v141, s[64:65] nt
	s_add_u32 s64, s64, 0x1000
	s_addc_u32 s65, s65, 0
	global_load_dword v16, v141, s[64:65] nt
	s_add_u32 s64, s64, 0x1000
	s_addc_u32 s65, s65, 0
	global_load_dword v17, v141, s[64:65] nt
	s_add_u32 s64, s64, 0x1000
	s_addc_u32 s65, s65, 0
	global_load_dword v18, v141, s[64:65] nt
; __device__ __forceinline__ unsigned pk2(float lo, float hi) { f32x2 v = {lo, hi}; bf16x2_t b = __builtin_convertvector(v, bf16x2_t); return __builtin_bit_cast(unsigned, b); }
; __device__ __forceinline__ void transpose_item(const float* __restrict__ W, int ldw, bf16_t* __restrict__ WT, int ldo, const float* __restrict__ g, int k0, int n0, int dstrow, int lane) {
;     ...
;     for (int i = 0; i < 64; ++i) v[i] = __builtin_nontemporal_load(src + (size_t)i * ldw);
;     if (g) {
; #pragma unroll
;         for (int i = 0; i < 64; ++i) v[i] *= g[k0 + i];
;     }
;     bf16_t* dst = WT + (size_t)dstrow * ldo + k0;
; #pragma unroll
;     for (int c = 0; c < 8; ++c) { u32x4 o; o.x = pk2(v[8 * c], v[8 * c + 1]); o.y = pk2(v[8 * c + 2], v[8 * c + 3]); o.z = pk2(v[8 * c + 4], v[8 * c + 5]); o.w = pk2(v[8 * c + 6], v[8 * c + 7]);
;         *(u32x4*)(dst + 8 * c) = o; }
	s_add_u32 s64, s64, 0x1000
	s_addc_u32 s65, s65, 0
	global_load_dword v19, v141, s[64:65] nt
	s_add_u32 s64, s64, 0x1000
	s_addc_u32 s65, s65, 0
	global_load_dword v20, v141, s[64:65] nt
	s_add_u32 s64, s64, 0x1000
	s_addc_u32 s65, s65, 0
	global_load_dword v21, v141, s[64:65] nt
	s_add_u32 s64, s64, 0x1000
	s_addc_u32 s65, s65, 0
	global_load_dword v22, v141, s[64:65] nt
	s_add_u32 s64, s64, 0x1000
	s_addc_u32 s65, s65, 0
	global_load_dword v23, v141, s[64:65] nt
	s_add_u32 s64, s64, 0x1000
	s_addc_u32 s65, s65, 0
	global_load_dword v24, v141, s[64:65] nt
	s_add_u32 s64, s64, 0x1000
	s_addc_u32 s65, s65, 0
	global_load_dword v25, v141, s[64:65] nt
	s_add_u32 s64, s64, 0x1000
	s_addc_u32 s65, s65, 0
	global_load_dword v26, v141, s[64:65] nt
	s_add_u32 s64, s64, 0x1000
	s_addc_u32 s65, s65, 0
	global_load_dword v27, v141, s[64:65] nt
	s_add_u32 s64, s64, 0x1000
	s_addc_u32 s65, s65, 0
	global_load_dword v28, v141, s[64:65] nt
	s_add_u32 s64, s64, 0x1000
	s_addc_u32 s65, s65, 0
	global_load_dword v29, v141, s[64:65] nt
	s_add_u32 s64, s64, 0x1000
	s_addc_u32 s65, s65, 0
	global_load_dword v30, v141, s[64:65] nt
	s_add_u32 s64, s64, 0x1000
	s_addc_u32 s65, s65, 0
	global_load_dword v31, v141, s[64:65] nt
	s_add_u32 s64, s64, 0x1000
	s_addc_u32 s65, s65, 0
	global_load_dword v32, v141, s[64:65] nt
	s_add_u32 s64, s64, 0x1000
	s_addc_u32 s65, s65, 0
	global_load_dword v33, v141, s[64:65] nt
	s_add_u32 s64, s64, 0x1000
	s_addc_u32 s65, s65, 0
	global_load_dword v34, v141, s[64:65] nt
	s_add_u32 s64, s64, 0x1000
	s_addc_u32 s65, s65, 0
	global_load_dword v35, v141, s[64:65] nt
	s_add_u32 s64, s64, 0x1000
	s_addc_u32 s65, s65, 0
	global_load_dword v36, v141, s[64:65] nt
	s_add_u32 s64, s64, 0x1000
	s_addc_u32 s65, s65, 0
	global_load_dword v37, v141, s[64:65] nt
	s_add_u32 s64, s64, 0x1000
	s_addc_u32 s65, s65, 0
	global_load_dword v38, v141, s[64:65] nt
	s_add_u32 s64, s64, 0x1000
	s_addc_u32 s65, s65, 0
	global_load_dword v39, v141, s[64:65] nt
	s_add_u32 s64, s64, 0x1000
	s_addc_u32 s65, s65, 0
	global_load_dword v40, v141, s[64:65] nt
	s_add_u32 s64, s64, 0x1000
	s_addc_u32 s65, s65, 0
	global_load_dword v41, v141, s[64:65] nt
	s_add_u32 s64, s64, 0x1000
	s_addc_u32 s65, s65, 0
	global_load_dword v42, v141, s[64:65] nt
	s_add_u32 s64, s64, 0x1000
	s_addc_u32 s65, s65, 0
	global_load_dword v43, v141, s[64:65] nt
	s_add_u32 s64, s64, 0x1000
	s_addc_u32 s65, s65, 0
	global_load_dword v44, v141, s[64:65] nt
	s_add_u32 s64, s64, 0x1000
	s_addc_u32 s65, s65, 0
	global_load_dword v45, v141, s[64:65] nt
	s_add_u32 s64, s64, 0x1000
	s_addc_u32 s65, s65, 0
	global_load_dword v46, v141, s[64:65] nt
	s_add_u32 s64, s64, 0x1000
	s_addc_u32 s65, s65, 0
	global_load_dword v47, v141, s[64:65] nt
	s_add_u32 s64, s64, 0x1000
	s_addc_u32 s65, s65, 0
	global_load_dword v48, v141, s[64:65] nt
	s_add_u32 s64, s64, 0x1000
	s_addc_u32 s65, s65, 0
	global_load_dword v49, v141, s[64:65] nt
	s_add_u32 s64, s64, 0x1000
	s_addc_u32 s65, s65, 0
	global_load_dword v50, v141, s[64:65] nt
	s_add_u32 s64, s64, 0x1000
	s_addc_u32 s65, s65, 0
	global_load_dword v51, v141, s[64:65] nt
	s_add_u32 s64, s64, 0x1000
	s_addc_u32 s65, s65, 0
	global_load_dword v52, v141, s[64:65] nt
	s_add_u32 s64, s64, 0x1000
	s_addc_u32 s65, s65, 0
	global_load_dword v53, v141, s[64:65] nt
	s_add_u32 s64, s64, 0x1000
	s_addc_u32 s65, s65, 0
	global_load_dword v54, v141, s[64:65] nt
	s_add_u32 s64, s64, 0x1000
	s_addc_u32 s65, s65, 0
	global_load_dword v55, v141, s[64:65] nt
	s_add_u32 s64, s64, 0x1000
	s_addc_u32 s65, s65, 0
	global_load_dword v56, v141, s[64:65] nt
	s_add_u32 s64, s64, 0x1000
	s_addc_u32 s65, s65, 0
	global_load_dword v57, v141, s[64:65] nt
	s_add_u32 s64, s64, 0x1000
	s_addc_u32 s65, s65, 0
	global_load_dword v58, v141, s[64:65] nt
	s_add_u32 s64, s64, 0x1000
	s_addc_u32 s65, s65, 0
	global_load_dword v59, v141, s[64:65] nt
	s_add_u32 s64, s64, 0x1000
	s_addc_u32 s65, s65, 0
	global_load_dword v60, v141, s[64:65] nt
	s_add_u32 s64, s64, 0x1000
	s_addc_u32 s65, s65, 0
	global_load_dword v61, v141, s[64:65] nt
	s_add_u32 s64, s64, 0x1000
	s_addc_u32 s65, s65, 0
	global_load_dword v62, v141, s[64:65] nt
	s_add_u32 s64, s64, 0x1000
	s_addc_u32 s65, s65, 0
	global_load_dword v63, v141, s[64:65] nt
	s_waitcnt vmcnt(0)
	v_cvt_pk_bf16_f32 v0, v0, v1
	v_cvt_pk_bf16_f32 v1, v2, v3
	v_cvt_pk_bf16_f32 v2, v4, v5
	v_cvt_pk_bf16_f32 v3, v6, v7
	v_cvt_pk_bf16_f32 v4, v8, v9
	v_cvt_pk_bf16_f32 v5, v10, v11
	v_cvt_pk_bf16_f32 v6, v12, v13
	v_cvt_pk_bf16_f32 v7, v14, v15
	v_cvt_pk_bf16_f32 v8, v16, v17
	v_cvt_pk_bf16_f32 v9, v18, v19
	v_cvt_pk_bf16_f32 v10, v20, v21
	v_cvt_pk_bf16_f32 v11, v22, v23
	v_cvt_pk_bf16_f32 v12, v24, v25
	v_cvt_pk_bf16_f32 v13, v26, v27
	v_cvt_pk_bf16_f32 v14, v28, v29
	v_cvt_pk_bf16_f32 v15, v30, v31
	v_cvt_pk_bf16_f32 v16, v32, v33
	v_cvt_pk_bf16_f32 v17, v34, v35
	v_cvt_pk_bf16_f32 v18, v36, v37
	v_cvt_pk_bf16_f32 v19, v38, v39
	v_cvt_pk_bf16_f32 v20, v40, v41
	v_cvt_pk_bf16_f32 v21, v42, v43
	v_cvt_pk_bf16_f32 v22, v44, v45
	v_cvt_pk_bf16_f32 v23, v46, v47
	v_cvt_pk_bf16_f32 v24, v48, v49
	v_cvt_pk_bf16_f32 v25, v50, v51
	v_cvt_pk_bf16_f32 v26, v52, v53
	v_cvt_pk_bf16_f32 v27, v54, v55
	v_cvt_pk_bf16_f32 v28, v56, v57
	v_cvt_pk_bf16_f32 v29, v58, v59
	v_cvt_pk_bf16_f32 v30, v60, v61
	v_cvt_pk_bf16_f32 v31, v62, v63
	global_store_dwordx4 v143, v[0:3], s[66:67]
	global_store_dwordx4 v143, v[4:7], s[66:67] offset:16
	global_store_dwordx4 v143, v[8:11], s[66:67] offset:32
	global_store_dwordx4 v143, v[12:15], s[66:67] offset:48
	global_store_dwordx4 v143, v[16:19], s[66:67] offset:64
	global_store_dwordx4 v143, v[20:23], s[66:67] offset:80
	global_store_dwordx4 v143, v[24:27], s[66:67] offset:96
	global_store_dwordx4 v143, v[28:31], s[66:67] offset:112
.Llt0_next:
	s_add_u32 s63, s63, s68
	s_branch .Llt0_loop

; __device__ __forceinline__ void transpose_item(const float* __restrict__ W, int ldw, bf16_t* __restrict__ WT, int ldo, const float* __restrict__ g, int k0, int n0, int dstrow, int lane) {
;     const float* src = W + (size_t)k0 * ldw + n0 + lane;
;     float v[64];
; #pragma unroll
;     for (int i = 0; i < 64; ++i) v[i] = __builtin_nontemporal_load(src + (size_t)i * ldw);
; __device__ __forceinline__ int win_dst(int n0) {
;     if (n0 < 1024) { const int ch = n0 & 511, gate = n0 >> 9; return 256 * (ch >> 7) + 128 * gate + (ch & 127); }
;     const int r = n0 - 1024, kind = r >> 9, hd = r & 511, head = hd >> 6, d = hd & 63;
;     return 1024 + kind * 512 + 256 * (head >> 2) + (((d >> 5) << 7) | ((head & 3) << 5) | (d & 31));
; }
.LBB0_732:
	s_cmp_lg_u32 s62, 0
	s_cbranch_scc1 .Llt1_done
	v_readfirstlane_b32 s4, v173
	s_nop 3
	s_lshr_b32 s4, s4, 6
	s_lshl_b32 s63, s76, 3
	s_add_u32 s63, s63, s4
	s_lshl_b32 s68, s33, 3
	s_cmp_gt_u32 s33, 0x20
	s_cbranch_scc0 .Llt1_loop0
	s_cmp_lt_u32 s76, 32
	s_cbranch_scc1 .Llt1_done
	s_sub_u32 s63, s63, 0x100
	s_sub_u32 s68, s68, 0x100
.Llt1_loop0:
.Llt1_loop:
	s_cmpk_lt_u32 s63, 0xb80
	s_cbranch_scc0 .Llt1_done
	s_mov_b32 s4, s63
	s_cmpk_lt_u32 s63, 0x280
	s_cbranch_scc0 .Llt1_n0
	s_lshr_b32 s2, s4, 2
	s_mul_i32 s2, s2, 0xcccd
	s_lshr_b32 s2, s2, 19
	s_mul_i32 s3, s2, 40
	s_sub_u32 s3, s4, s3
	s_load_dwordx2 s[64:65], s[0:1], 0x30
	s_load_dwordx2 s[66:67], s[0:1], 0x98
	v_and_b32_e32 v141, 32, v191
	v_lshl_add_u32 v141, s3, 6, v141
	s_cmp_lt_u32 s3, 16
	s_cbranch_scc0 .Llt1A_qkv
	v_and_b32_e32 v142, 0x1ff, v141
	v_lshrrev_b32_e32 v148, 9, v141
	v_lshrrev_b32_e32 v149, 7, v142
	v_and_b32_e32 v142, 0x7f, v142
	v_lshl_add_u32 v142, v149, 8, v142
	v_lshl_add_u32 v142, v148, 7, v142
	s_branch .Llt1A_row
.Llt1A_qkv:
	v_add_u32_e32 v141, 0xfffffc00, v141
	v_lshrrev_b32_e32 v148, 9, v141
	v_and_b32_e32 v141, 0x1ff, v141
	v_lshrrev_b32_e32 v149, 6, v141
	v_and_b32_e32 v141, 63, v141
	v_lshlrev_b32_e32 v142, 9, v148
	v_add_u32_e32 v142, 0x400, v142
	v_lshrrev_b32_e32 v148, 2, v149
	v_lshl_add_u32 v142, v148, 8, v142
	v_lshrrev_b32_e32 v148, 5, v141
	v_lshl_add_u32 v142, v148, 7, v142
	v_and_b32_e32 v149, 3, v149
	v_lshl_add_u32 v142, v149, 5, v142
.Llt1A_row:
	v_and_b32_e32 v141, 31, v191
	v_add_u32_e32 v142, v142, v141
	v_lshlrev_b32_e32 v143, 11, v142
	s_lshl_b32 s4, s2, 7
	v_add_u32_e32 v143, s4, v143
	v_lshlrev_b32_e32 v141, 2, v191
	s_waitcnt lgkmcnt(0)
	s_add_u32 s66, s66, 0x1a00000
	s_addc_u32 s67, s67, 0
	s_mul_i32 s4, s2, 0xa0000
	s_add_u32 s4, s4, 0xa00000
	s_add_u32 s64, s64, s4
	s_addc_u32 s65, s65, 0
	s_lshl_b32 s4, s3, 8
	s_add_u32 s64, s64, s4
	s_addc_u32 s65, s65, 0
	s_lshl_b32 s4, s2, 8
	s_load_dwordx2 s[2:3], s[0:1], 0x28
	global_load_dword v0, v141, s[64:65] nt
	s_add_u32 s64, s64, 0x2800
	s_addc_u32 s65, s65, 0
	global_load_dword v1, v141, s[64:65] nt
	s_add_u32 s64, s64, 0x2800
	s_addc_u32 s65, s65, 0
	global_load_dword v2, v141, s[64:65] nt
	s_add_u32 s64, s64, 0x2800
	s_addc_u32 s65, s65, 0
	global_load_dword v3, v141, s[64:65] nt
	s_add_u32 s64, s64, 0x2800
	s_addc_u32 s65, s65, 0
	global_load_dword v4, v141, s[64:65] nt
	s_add_u32 s64, s64, 0x2800
	s_addc_u32 s65, s65, 0
	global_load_dword v5, v141, s[64:65] nt
	s_add_u32 s64, s64, 0x2800
	s_addc_u32 s65, s65, 0
	global_load_dword v6, v141, s[64:65] nt
	s_add_u32 s64, s64, 0x2800
	s_addc_u32 s65, s65, 0
	global_load_dword v7, v141, s[64:65] nt
	s_add_u32 s64, s64, 0x2800
	s_addc_u32 s65, s65, 0
	global_load_dword v8, v141, s[64:65] nt
	s_add_u32 s64, s64, 0x2800
	s_addc_u32 s65, s65, 0
	global_load_dword v9, v141, s[64:65] nt
	s_add_u32 s64, s64, 0x2800
	s_addc_u32 s65, s65, 0
	global_load_dword v10, v141, s[64:65] nt
	s_add_u32 s64, s64, 0x2800
	s_addc_u32 s65, s65, 0
	global_load_dword v11, v141, s[64:65] nt
	s_add_u32 s64, s64, 0x2800
	s_addc_u32 s65, s65, 0
	global_load_dword v12, v141, s[64:65] nt
	s_add_u32 s64, s64, 0x2800
	s_addc_u32 s65, s65, 0
	global_load_dword v13, v141, s[64:65] nt
	s_add_u32 s64, s64, 0x2800
	s_addc_u32 s65, s65, 0
	global_load_dword v14, v141, s[64:65] nt
	s_add_u32 s64, s64, 0x2800
	s_addc_u32 s65, s65, 0
	global_load_dword v15, v141, s[64:65] nt
	s_add_u32 s64, s64, 0x2800
	s_addc_u32 s65, s65, 0
	global_load_dword v16, v141, s[64:65] nt
	s_add_u32 s64, s64, 0x2800
	s_addc_u32 s65, s65, 0
	global_load_dword v17, v141, s[64:65] nt
	s_add_u32 s64, s64, 0x2800
	s_addc_u32 s65, s65, 0
	global_load_dword v18, v141, s[64:65] nt
	s_add_u32 s64, s64, 0x2800
	s_addc_u32 s65, s65, 0
	global_load_dword v19, v141, s[64:65] nt
	s_add_u32 s64, s64, 0x2800
	s_addc_u32 s65, s65, 0
	global_load_dword v20, v141, s[64:65] nt
	s_add_u32 s64, s64, 0x2800
	s_addc_u32 s65, s65, 0
	global_load_dword v21, v141, s[64:65] nt
	s_add_u32 s64, s64, 0x2800
	s_addc_u32 s65, s65, 0
	global_load_dword v22, v141, s[64:65] nt
	s_add_u32 s64, s64, 0x2800
	s_addc_u32 s65, s65, 0
	global_load_dword v23, v141, s[64:65] nt
	s_add_u32 s64, s64, 0x2800
	s_addc_u32 s65, s65, 0
	global_load_dword v24, v141, s[64:65] nt
	s_add_u32 s64, s64, 0x2800
	s_addc_u32 s65, s65, 0
	global_load_dword v25, v141, s[64:65] nt
	s_add_u32 s64, s64, 0x2800
	s_addc_u32 s65, s65, 0
	global_load_dword v26, v141, s[64:65] nt
	s_add_u32 s64, s64, 0x2800
	s_addc_u32 s65, s65, 0
	global_load_dword v27, v141, s[64:65] nt
	s_add_u32 s64, s64, 0x2800
	s_addc_u32 s65, s65, 0
	global_load_dword v28, v141, s[64:65] nt
	s_add_u32 s64, s64, 0x2800
	s_addc_u32 s65, s65, 0
	global_load_dword v29, v141, s[64:65] nt
	s_add_u32 s64, s64, 0x2800
	s_addc_u32 s65, s65, 0
	global_load_dword v30, v141, s[64:65] nt
	s_add_u32 s64, s64, 0x2800
	s_addc_u32 s65, s65, 0
	global_load_dword v31, v141, s[64:65] nt
	s_add_u32 s64, s64, 0x2800
	s_addc_u32 s65, s65, 0
	global_load_dword v32, v141, s[64:65] nt
	s_add_u32 s64, s64, 0x2800
	s_addc_u32 s65, s65, 0
	global_load_dword v33, v141, s[64:65] nt
	s_add_u32 s64, s64, 0x2800
	s_addc_u32 s65, s65, 0
	global_load_dword v34, v141, s[64:65] nt
	s_add_u32 s64, s64, 0x2800
	s_addc_u32 s65, s65, 0
	global_load_dword v35, v141, s[64:65] nt
	s_add_u32 s64, s64, 0x2800
	s_addc_u32 s65, s65, 0
	global_load_dword v36, v141, s[64:65] nt
	s_add_u32 s64, s64, 0x2800
	s_addc_u32 s65, s65, 0
	global_load_dword v37, v141, s[64:65] nt
	s_add_u32 s64, s64, 0x2800
	s_addc_u32 s65, s65, 0
	global_load_dword v38, v141, s[64:65] nt
	s_add_u32 s64, s64, 0x2800
	s_addc_u32 s65, s65, 0
; __device__ __forceinline__ void transpose_item(const float* __restrict__ W, int ldw, bf16_t* __restrict__ WT, int ldo, const float* __restrict__ g, int k0, int n0, int dstrow, int lane) {
;     ...
;     for (int i = 0; i < 64; ++i) v[i] = __builtin_nontemporal_load(src + (size_t)i * ldw);
;     if (g) {
; #pragma unroll
;         for (int i = 0; i < 64; ++i) v[i] *= g[k0 + i];
	global_load_dword v39, v141, s[64:65] nt
	s_add_u32 s64, s64, 0x2800
	s_addc_u32 s65, s65, 0
	global_load_dword v40, v141, s[64:65] nt
	s_add_u32 s64, s64, 0x2800
	s_addc_u32 s65, s65, 0
	global_load_dword v41, v141, s[64:65] nt
	s_add_u32 s64, s64, 0x2800
	s_addc_u32 s65, s65, 0
	global_load_dword v42, v141, s[64:65] nt
	s_add_u32 s64, s64, 0x2800
	s_addc_u32 s65, s65, 0
	global_load_dword v43, v141, s[64:65] nt
	s_add_u32 s64, s64, 0x2800
	s_addc_u32 s65, s65, 0
	global_load_dword v44, v141, s[64:65] nt
	s_add_u32 s64, s64, 0x2800
	s_addc_u32 s65, s65, 0
	global_load_dword v45, v141, s[64:65] nt
	s_add_u32 s64, s64, 0x2800
	s_addc_u32 s65, s65, 0
	global_load_dword v46, v141, s[64:65] nt
	s_add_u32 s64, s64, 0x2800
	s_addc_u32 s65, s65, 0
	global_load_dword v47, v141, s[64:65] nt
	s_add_u32 s64, s64, 0x2800
	s_addc_u32 s65, s65, 0
	global_load_dword v48, v141, s[64:65] nt
	s_add_u32 s64, s64, 0x2800
	s_addc_u32 s65, s65, 0
	global_load_dword v49, v141, s[64:65] nt
	s_add_u32 s64, s64, 0x2800
	s_addc_u32 s65, s65, 0
	global_load_dword v50, v141, s[64:65] nt
	s_add_u32 s64, s64, 0x2800
	s_addc_u32 s65, s65, 0
	global_load_dword v51, v141, s[64:65] nt
	s_add_u32 s64, s64, 0x2800
	s_addc_u32 s65, s65, 0
	global_load_dword v52, v141, s[64:65] nt
	s_add_u32 s64, s64, 0x2800
	s_addc_u32 s65, s65, 0
	global_load_dword v53, v141, s[64:65] nt
	s_add_u32 s64, s64, 0x2800
	s_addc_u32 s65, s65, 0
	global_load_dword v54, v141, s[64:65] nt
	s_add_u32 s64, s64, 0x2800
	s_addc_u32 s65, s65, 0
	global_load_dword v55, v141, s[64:65] nt
	s_add_u32 s64, s64, 0x2800
	s_addc_u32 s65, s65, 0
	global_load_dword v56, v141, s[64:65] nt
	s_add_u32 s64, s64, 0x2800
	s_addc_u32 s65, s65, 0
	global_load_dword v57, v141, s[64:65] nt
	s_add_u32 s64, s64, 0x2800
	s_addc_u32 s65, s65, 0
	global_load_dword v58, v141, s[64:65] nt
	s_add_u32 s64, s64, 0x2800
	s_addc_u32 s65, s65, 0
	global_load_dword v59, v141, s[64:65] nt
	s_add_u32 s64, s64, 0x2800
	s_addc_u32 s65, s65, 0
	global_load_dword v60, v141, s[64:65] nt
	s_add_u32 s64, s64, 0x2800
	s_addc_u32 s65, s65, 0
	global_load_dword v61, v141, s[64:65] nt
	s_add_u32 s64, s64, 0x2800
	s_addc_u32 s65, s65, 0
	global_load_dword v62, v141, s[64:65] nt
	s_add_u32 s64, s64, 0x2800
	s_addc_u32 s65, s65, 0
	global_load_dword v63, v141, s[64:65] nt
	s_waitcnt lgkmcnt(0)
	s_add_u32 s4, s4, 0x1000
	s_add_u32 s2, s2, s4
	s_addc_u32 s3, s3, 0
	global_load_dword v64, v153, s[2:3]
	global_load_dword v65, v153, s[2:3] offset:4
	global_load_dword v66, v153, s[2:3] offset:8
	global_load_dword v67, v153, s[2:3] offset:12
	global_load_dword v68, v153, s[2:3] offset:16
	global_load_dword v69, v153, s[2:3] offset:20
	global_load_dword v70, v153, s[2:3] offset:24
	global_load_dword v71, v153, s[2:3] offset:28
	global_load_dword v72, v153, s[2:3] offset:32
	global_load_dword v73, v153, s[2:3] offset:36
	global_load_dword v74, v153, s[2:3] offset:40
	global_load_dword v75, v153, s[2:3] offset:44
	global_load_dword v76, v153, s[2:3] offset:48
	global_load_dword v77, v153, s[2:3] offset:52
	global_load_dword v78, v153, s[2:3] offset:56
	global_load_dword v79, v153, s[2:3] offset:60
	global_load_dword v80, v153, s[2:3] offset:64
	global_load_dword v81, v153, s[2:3] offset:68
	global_load_dword v82, v153, s[2:3] offset:72
	global_load_dword v83, v153, s[2:3] offset:76
	global_load_dword v84, v153, s[2:3] offset:80
	global_load_dword v85, v153, s[2:3] offset:84
	global_load_dword v86, v153, s[2:3] offset:88
	global_load_dword v87, v153, s[2:3] offset:92
	global_load_dword v88, v153, s[2:3] offset:96
	global_load_dword v89, v153, s[2:3] offset:100
	global_load_dword v90, v153, s[2:3] offset:104
	global_load_dword v91, v153, s[2:3] offset:108
	global_load_dword v92, v153, s[2:3] offset:112
	global_load_dword v93, v153, s[2:3] offset:116
	global_load_dword v94, v153, s[2:3] offset:120
	global_load_dword v95, v153, s[2:3] offset:124
	global_load_dword v96, v153, s[2:3] offset:128
	global_load_dword v97, v153, s[2:3] offset:132
	global_load_dword v98, v153, s[2:3] offset:136
	global_load_dword v99, v153, s[2:3] offset:140
	global_load_dword v100, v153, s[2:3] offset:144
	global_load_dword v101, v153, s[2:3] offset:148
	global_load_dword v102, v153, s[2:3] offset:152
	global_load_dword v103, v153, s[2:3] offset:156
	global_load_dword v104, v153, s[2:3] offset:160
	global_load_dword v105, v153, s[2:3] offset:164
	global_load_dword v106, v153, s[2:3] offset:168
	global_load_dword v107, v153, s[2:3] offset:172
	global_load_dword v108, v153, s[2:3] offset:176
	global_load_dword v109, v153, s[2:3] offset:180
	global_load_dword v110, v153, s[2:3] offset:184
	global_load_dword v111, v153, s[2:3] offset:188
	global_load_dword v112, v153, s[2:3] offset:192
	global_load_dword v113, v153, s[2:3] offset:196
	global_load_dword v114, v153, s[2:3] offset:200
	global_load_dword v115, v153, s[2:3] offset:204
	global_load_dword v116, v153, s[2:3] offset:208
	global_load_dword v117, v153, s[2:3] offset:212
	global_load_dword v118, v153, s[2:3] offset:216
	global_load_dword v119, v153, s[2:3] offset:220
	global_load_dword v120, v153, s[2:3] offset:224
	global_load_dword v121, v153, s[2:3] offset:228
	global_load_dword v122, v153, s[2:3] offset:232
	global_load_dword v123, v153, s[2:3] offset:236
	global_load_dword v124, v153, s[2:3] offset:240
	global_load_dword v125, v153, s[2:3] offset:244
	global_load_dword v126, v153, s[2:3] offset:248
	global_load_dword v127, v153, s[2:3] offset:252
	s_waitcnt vmcnt(0)
; __device__ __forceinline__ unsigned pk2(float lo, float hi) { f32x2 v = {lo, hi}; bf16x2_t b = __builtin_convertvector(v, bf16x2_t); return __builtin_bit_cast(unsigned, b); }
; #define KIN(i) ((const float*)kptr<float>(i))
; __device__ __forceinline__ void transpose_item(const float* __restrict__ W, int ldw, bf16_t* __restrict__ WT, int ldo, const float* __restrict__ g, int k0, int n0, int dstrow, int lane) {
;     ...
;         for (int i = 0; i < 64; ++i) v[i] *= g[k0 + i];
;     }
;     bf16_t* dst = WT + (size_t)dstrow * ldo + k0;
; #pragma unroll
;     for (int c = 0; c < 8; ++c) { u32x4 o; o.x = pk2(v[8 * c], v[8 * c + 1]); o.y = pk2(v[8 * c + 2], v[8 * c + 3]); o.z = pk2(v[8 * c + 4], v[8 * c + 5]); o.w = pk2(v[8 * c + 6], v[8 * c + 7]);
;         *(u32x4*)(dst + 8 * c) = o; }
; __global__ void __launch_bounds__(NWAVES * 64, 2) fwd_mega(Args args) {
;     ...
;                 if (r < I_OUT) { const int kb = r / 16, nb = r % 16; transpose_item(KIN(14) + (size_t)l * DM * DM, DM, (bf16_t*)(wl + (kb < 8 ? W_OUTA : W_OUT2)), DM, nullptr, 64 * kb, 64 * nb, 64 * nb + lane, lane); continue; } r -= I_OUT;
	v_mul_f32_e32 v0, v0, v64
	v_mul_f32_e32 v1, v1, v65
	v_mul_f32_e32 v2, v2, v66
	v_mul_f32_e32 v3, v3, v67
	v_mul_f32_e32 v4, v4, v68
	v_mul_f32_e32 v5, v5, v69
	v_mul_f32_e32 v6, v6, v70
	v_mul_f32_e32 v7, v7, v71
	v_mul_f32_e32 v8, v8, v72
	v_mul_f32_e32 v9, v9, v73
	v_mul_f32_e32 v10, v10, v74
	v_mul_f32_e32 v11, v11, v75
	v_mul_f32_e32 v12, v12, v76
	v_mul_f32_e32 v13, v13, v77
	v_mul_f32_e32 v14, v14, v78
	v_mul_f32_e32 v15, v15, v79
	v_mul_f32_e32 v16, v16, v80
	v_mul_f32_e32 v17, v17, v81
	v_mul_f32_e32 v18, v18, v82
	v_mul_f32_e32 v19, v19, v83
	v_mul_f32_e32 v20, v20, v84
	v_mul_f32_e32 v21, v21, v85
	v_mul_f32_e32 v22, v22, v86
	v_mul_f32_e32 v23, v23, v87
	v_mul_f32_e32 v24, v24, v88
	v_mul_f32_e32 v25, v25, v89
	v_mul_f32_e32 v26, v26, v90
	v_mul_f32_e32 v27, v27, v91
	v_mul_f32_e32 v28, v28, v92
	v_mul_f32_e32 v29, v29, v93
	v_mul_f32_e32 v30, v30, v94
	v_mul_f32_e32 v31, v31, v95
	v_mul_f32_e32 v32, v32, v96
	v_mul_f32_e32 v33, v33, v97
	v_mul_f32_e32 v34, v34, v98
	v_mul_f32_e32 v35, v35, v99
	v_mul_f32_e32 v36, v36, v100
	v_mul_f32_e32 v37, v37, v101
	v_mul_f32_e32 v38, v38, v102
	v_mul_f32_e32 v39, v39, v103
	v_mul_f32_e32 v40, v40, v104
	v_mul_f32_e32 v41, v41, v105
	v_mul_f32_e32 v42, v42, v106
	v_mul_f32_e32 v43, v43, v107
	v_mul_f32_e32 v44, v44, v108
	v_mul_f32_e32 v45, v45, v109
	v_mul_f32_e32 v46, v46, v110
	v_mul_f32_e32 v47, v47, v111
	v_mul_f32_e32 v48, v48, v112
	v_mul_f32_e32 v49, v49, v113
	v_mul_f32_e32 v50, v50, v114
	v_mul_f32_e32 v51, v51, v115
	v_mul_f32_e32 v52, v52, v116
	v_mul_f32_e32 v53, v53, v117
	v_mul_f32_e32 v54, v54, v118
	v_mul_f32_e32 v55, v55, v119
	v_mul_f32_e32 v56, v56, v120
	v_mul_f32_e32 v57, v57, v121
	v_mul_f32_e32 v58, v58, v122
	v_mul_f32_e32 v59, v59, v123
	v_mul_f32_e32 v60, v60, v124
	v_mul_f32_e32 v61, v61, v125
	v_mul_f32_e32 v62, v62, v126
	v_mul_f32_e32 v63, v63, v127
	v_cvt_pk_bf16_f32 v0, v0, v1
	v_cvt_pk_bf16_f32 v1, v2, v3
	v_cvt_pk_bf16_f32 v2, v4, v5
	v_cvt_pk_bf16_f32 v3, v6, v7
	v_cvt_pk_bf16_f32 v4, v8, v9
	v_cvt_pk_bf16_f32 v5, v10, v11
	v_cvt_pk_bf16_f32 v6, v12, v13
	v_cvt_pk_bf16_f32 v7, v14, v15
	v_cvt_pk_bf16_f32 v8, v16, v17
	v_cvt_pk_bf16_f32 v9, v18, v19
	v_cvt_pk_bf16_f32 v10, v20, v21
	v_cvt_pk_bf16_f32 v11, v22, v23
	v_cvt_pk_bf16_f32 v12, v24, v25
	v_cvt_pk_bf16_f32 v13, v26, v27
	v_cvt_pk_bf16_f32 v14, v28, v29
	v_cvt_pk_bf16_f32 v15, v30, v31
	v_cvt_pk_bf16_f32 v16, v32, v33
	v_cvt_pk_bf16_f32 v17, v34, v35
	v_cvt_pk_bf16_f32 v18, v36, v37
	v_cvt_pk_bf16_f32 v19, v38, v39
	v_cvt_pk_bf16_f32 v20, v40, v41
	v_cvt_pk_bf16_f32 v21, v42, v43
	v_cvt_pk_bf16_f32 v22, v44, v45
	v_cvt_pk_bf16_f32 v23, v46, v47
	v_cvt_pk_bf16_f32 v24, v48, v49
	v_cvt_pk_bf16_f32 v25, v50, v51
	v_cvt_pk_bf16_f32 v26, v52, v53
	v_cvt_pk_bf16_f32 v27, v54, v55
	v_cvt_pk_bf16_f32 v28, v56, v57
	v_cvt_pk_bf16_f32 v29, v58, v59
	v_cvt_pk_bf16_f32 v30, v60, v61
	v_cvt_pk_bf16_f32 v31, v62, v63
	global_store_dwordx4 v143, v[0:3], s[66:67]
	global_store_dwordx4 v143, v[4:7], s[66:67] offset:16
	global_store_dwordx4 v143, v[8:11], s[66:67] offset:32
	global_store_dwordx4 v143, v[12:15], s[66:67] offset:48
	global_store_dwordx4 v143, v[16:19], s[66:67] offset:64
	global_store_dwordx4 v143, v[20:23], s[66:67] offset:80
	global_store_dwordx4 v143, v[24:27], s[66:67] offset:96
	global_store_dwordx4 v143, v[28:31], s[66:67] offset:112
	s_branch .Llt1_next
.Llt1_n0:
	s_cmpk_lt_u32 s63, 0x380
	s_cbranch_scc0 .Llt1_n1
	s_sub_u32 s4, s63, 0x280
	s_lshr_b32 s2, s4, 4
	s_and_b32 s3, s4, 15
	s_load_dwordx2 s[64:65], s[0:1], 0x70
	s_load_dwordx2 s[66:67], s[0:1], 0x98
	v_lshl_add_u32 v142, s3, 6, v191
	v_lshlrev_b32_e32 v143, 11, v142
	s_lshl_b32 s4, s2, 7
	v_add_u32_e32 v143, s4, v143
	v_lshlrev_b32_e32 v141, 2, v191
	s_waitcnt lgkmcnt(0)
	s_mov_b32 s4, 0x2200000
	s_cmp_lt_u32 s2, 8
	s_cselect_b32 s4, 0x2000000, s4
	s_add_u32 s66, s66, s4
	s_addc_u32 s67, s67, 0
	s_mul_i32 s4, s2, 0x40000
	s_add_u32 s4, s4, 0x400000
	s_add_u32 s64, s64, s4
	s_addc_u32 s65, s65, 0
	s_lshl_b32 s4, s3, 8
	s_add_u32 s64, s64, s4
	s_addc_u32 s65, s65, 0
	global_load_dword v0, v141, s[64:65] nt
	s_add_u32 s64, s64, 0x1000
	s_addc_u32 s65, s65, 0
	global_load_dword v1, v141, s[64:65] nt
	s_add_u32 s64, s64, 0x1000
	s_addc_u32 s65, s65, 0
	global_load_dword v2, v141, s[64:65] nt
	s_add_u32 s64, s64, 0x1000
	s_addc_u32 s65, s65, 0
	global_load_dword v3, v141, s[64:65] nt
	s_add_u32 s64, s64, 0x1000
	s_addc_u32 s65, s65, 0
	global_load_dword v4, v141, s[64:65] nt
	s_add_u32 s64, s64, 0x1000
	s_addc_u32 s65, s65, 0
	global_load_dword v5, v141, s[64:65] nt
	s_add_u32 s64, s64, 0x1000
	s_addc_u32 s65, s65, 0
	global_load_dword v6, v141, s[64:65] nt
	s_add_u32 s64, s64, 0x1000
	s_addc_u32 s65, s65, 0
	global_load_dword v7, v141, s[64:65] nt
	s_add_u32 s64, s64, 0x1000
	s_addc_u32 s65, s65, 0
	global_load_dword v8, v141, s[64:65] nt
	s_add_u32 s64, s64, 0x1000
	s_addc_u32 s65, s65, 0
	global_load_dword v9, v141, s[64:65] nt
	s_add_u32 s64, s64, 0x1000
	s_addc_u32 s65, s65, 0
	global_load_dword v10, v141, s[64:65] nt
	s_add_u32 s64, s64, 0x1000
	s_addc_u32 s65, s65, 0
	global_load_dword v11, v141, s[64:65] nt
	s_add_u32 s64, s64, 0x1000
	s_addc_u32 s65, s65, 0
	global_load_dword v12, v141, s[64:65] nt
	s_add_u32 s64, s64, 0x1000
	s_addc_u32 s65, s65, 0
	global_load_dword v13, v141, s[64:65] nt
	s_add_u32 s64, s64, 0x1000
	s_addc_u32 s65, s65, 0
	global_load_dword v14, v141, s[64:65] nt
	s_add_u32 s64, s64, 0x1000
	s_addc_u32 s65, s65, 0
	global_load_dword v15, v141, s[64:65] nt
	s_add_u32 s64, s64, 0x1000
	s_addc_u32 s65, s65, 0
	global_load_dword v16, v141, s[64:65] nt
	s_add_u32 s64, s64, 0x1000
	s_addc_u32 s65, s65, 0
; __device__ __forceinline__ unsigned pk2(float lo, float hi) { f32x2 v = {lo, hi}; bf16x2_t b = __builtin_convertvector(v, bf16x2_t); return __builtin_bit_cast(unsigned, b); }
; __device__ __forceinline__ void transpose_item(const float* __restrict__ W, int ldw, bf16_t* __restrict__ WT, int ldo, const float* __restrict__ g, int k0, int n0, int dstrow, int lane) {
;     ...
;     for (int i = 0; i < 64; ++i) v[i] = __builtin_nontemporal_load(src + (size_t)i * ldw);
;     if (g) {
; #pragma unroll
;         for (int i = 0; i < 64; ++i) v[i] *= g[k0 + i];
;     }
;     bf16_t* dst = WT + (size_t)dstrow * ldo + k0;
; #pragma unroll
;     for (int c = 0; c < 8; ++c) { u32x4 o; o.x = pk2(v[8 * c], v[8 * c + 1]); o.y = pk2(v[8 * c + 2], v[8 * c + 3]); o.z = pk2(v[8 * c + 4], v[8 * c + 5]); o.w = pk2(v[8 * c + 6], v[8 * c + 7]);
;         *(u32x4*)(dst + 8 * c) = o; }
	global_load_dword v17, v141, s[64:65] nt
	s_add_u32 s64, s64, 0x1000
	s_addc_u32 s65, s65, 0
	global_load_dword v18, v141, s[64:65] nt
	s_add_u32 s64, s64, 0x1000
	s_addc_u32 s65, s65, 0
	global_load_dword v19, v141, s[64:65] nt
	s_add_u32 s64, s64, 0x1000
	s_addc_u32 s65, s65, 0
	global_load_dword v20, v141, s[64:65] nt
	s_add_u32 s64, s64, 0x1000
	s_addc_u32 s65, s65, 0
	global_load_dword v21, v141, s[64:65] nt
	s_add_u32 s64, s64, 0x1000
	s_addc_u32 s65, s65, 0
	global_load_dword v22, v141, s[64:65] nt
	s_add_u32 s64, s64, 0x1000
	s_addc_u32 s65, s65, 0
	global_load_dword v23, v141, s[64:65] nt
	s_add_u32 s64, s64, 0x1000
	s_addc_u32 s65, s65, 0
	global_load_dword v24, v141, s[64:65] nt
	s_add_u32 s64, s64, 0x1000
	s_addc_u32 s65, s65, 0
	global_load_dword v25, v141, s[64:65] nt
	s_add_u32 s64, s64, 0x1000
	s_addc_u32 s65, s65, 0
	global_load_dword v26, v141, s[64:65] nt
	s_add_u32 s64, s64, 0x1000
	s_addc_u32 s65, s65, 0
	global_load_dword v27, v141, s[64:65] nt
	s_add_u32 s64, s64, 0x1000
	s_addc_u32 s65, s65, 0
	global_load_dword v28, v141, s[64:65] nt
	s_add_u32 s64, s64, 0x1000
	s_addc_u32 s65, s65, 0
	global_load_dword v29, v141, s[64:65] nt
	s_add_u32 s64, s64, 0x1000
	s_addc_u32 s65, s65, 0
	global_load_dword v30, v141, s[64:65] nt
	s_add_u32 s64, s64, 0x1000
	s_addc_u32 s65, s65, 0
	global_load_dword v31, v141, s[64:65] nt
	s_add_u32 s64, s64, 0x1000
	s_addc_u32 s65, s65, 0
	global_load_dword v32, v141, s[64:65] nt
	s_add_u32 s64, s64, 0x1000
	s_addc_u32 s65, s65, 0
	global_load_dword v33, v141, s[64:65] nt
	s_add_u32 s64, s64, 0x1000
	s_addc_u32 s65, s65, 0
	global_load_dword v34, v141, s[64:65] nt
	s_add_u32 s64, s64, 0x1000
	s_addc_u32 s65, s65, 0
	global_load_dword v35, v141, s[64:65] nt
	s_add_u32 s64, s64, 0x1000
	s_addc_u32 s65, s65, 0
	global_load_dword v36, v141, s[64:65] nt
	s_add_u32 s64, s64, 0x1000
	s_addc_u32 s65, s65, 0
	global_load_dword v37, v141, s[64:65] nt
	s_add_u32 s64, s64, 0x1000
	s_addc_u32 s65, s65, 0
	global_load_dword v38, v141, s[64:65] nt
	s_add_u32 s64, s64, 0x1000
	s_addc_u32 s65, s65, 0
	global_load_dword v39, v141, s[64:65] nt
	s_add_u32 s64, s64, 0x1000
	s_addc_u32 s65, s65, 0
	global_load_dword v40, v141, s[64:65] nt
	s_add_u32 s64, s64, 0x1000
	s_addc_u32 s65, s65, 0
	global_load_dword v41, v141, s[64:65] nt
	s_add_u32 s64, s64, 0x1000
	s_addc_u32 s65, s65, 0
	global_load_dword v42, v141, s[64:65] nt
	s_add_u32 s64, s64, 0x1000
	s_addc_u32 s65, s65, 0
	global_load_dword v43, v141, s[64:65] nt
	s_add_u32 s64, s64, 0x1000
	s_addc_u32 s65, s65, 0
	global_load_dword v44, v141, s[64:65] nt
	s_add_u32 s64, s64, 0x1000
	s_addc_u32 s65, s65, 0
	global_load_dword v45, v141, s[64:65] nt
	s_add_u32 s64, s64, 0x1000
	s_addc_u32 s65, s65, 0
	global_load_dword v46, v141, s[64:65] nt
	s_add_u32 s64, s64, 0x1000
	s_addc_u32 s65, s65, 0
	global_load_dword v47, v141, s[64:65] nt
	s_add_u32 s64, s64, 0x1000
	s_addc_u32 s65, s65, 0
	global_load_dword v48, v141, s[64:65] nt
	s_add_u32 s64, s64, 0x1000
	s_addc_u32 s65, s65, 0
	global_load_dword v49, v141, s[64:65] nt
	s_add_u32 s64, s64, 0x1000
	s_addc_u32 s65, s65, 0
	global_load_dword v50, v141, s[64:65] nt
	s_add_u32 s64, s64, 0x1000
	s_addc_u32 s65, s65, 0
	global_load_dword v51, v141, s[64:65] nt
	s_add_u32 s64, s64, 0x1000
	s_addc_u32 s65, s65, 0
	global_load_dword v52, v141, s[64:65] nt
	s_add_u32 s64, s64, 0x1000
	s_addc_u32 s65, s65, 0
	global_load_dword v53, v141, s[64:65] nt
	s_add_u32 s64, s64, 0x1000
	s_addc_u32 s65, s65, 0
	global_load_dword v54, v141, s[64:65] nt
	s_add_u32 s64, s64, 0x1000
	s_addc_u32 s65, s65, 0
	global_load_dword v55, v141, s[64:65] nt
	s_add_u32 s64, s64, 0x1000
	s_addc_u32 s65, s65, 0
	global_load_dword v56, v141, s[64:65] nt
	s_add_u32 s64, s64, 0x1000
	s_addc_u32 s65, s65, 0
	global_load_dword v57, v141, s[64:65] nt
	s_add_u32 s64, s64, 0x1000
	s_addc_u32 s65, s65, 0
	global_load_dword v58, v141, s[64:65] nt
	s_add_u32 s64, s64, 0x1000
	s_addc_u32 s65, s65, 0
	global_load_dword v59, v141, s[64:65] nt
	s_add_u32 s64, s64, 0x1000
	s_addc_u32 s65, s65, 0
	global_load_dword v60, v141, s[64:65] nt
	s_add_u32 s64, s64, 0x1000
	s_addc_u32 s65, s65, 0
	global_load_dword v61, v141, s[64:65] nt
	s_add_u32 s64, s64, 0x1000
	s_addc_u32 s65, s65, 0
	global_load_dword v62, v141, s[64:65] nt
	s_add_u32 s64, s64, 0x1000
	s_addc_u32 s65, s65, 0
	global_load_dword v63, v141, s[64:65] nt
	s_waitcnt vmcnt(0)
	v_cvt_pk_bf16_f32 v0, v0, v1
	v_cvt_pk_bf16_f32 v1, v2, v3
	v_cvt_pk_bf16_f32 v2, v4, v5
	v_cvt_pk_bf16_f32 v3, v6, v7
	v_cvt_pk_bf16_f32 v4, v8, v9
	v_cvt_pk_bf16_f32 v5, v10, v11
	v_cvt_pk_bf16_f32 v6, v12, v13
	v_cvt_pk_bf16_f32 v7, v14, v15
	v_cvt_pk_bf16_f32 v8, v16, v17
	v_cvt_pk_bf16_f32 v9, v18, v19
	v_cvt_pk_bf16_f32 v10, v20, v21
	v_cvt_pk_bf16_f32 v11, v22, v23
	v_cvt_pk_bf16_f32 v12, v24, v25
	v_cvt_pk_bf16_f32 v13, v26, v27
	v_cvt_pk_bf16_f32 v14, v28, v29
	v_cvt_pk_bf16_f32 v15, v30, v31
	v_cvt_pk_bf16_f32 v16, v32, v33
	v_cvt_pk_bf16_f32 v17, v34, v35
	v_cvt_pk_bf16_f32 v18, v36, v37
	v_cvt_pk_bf16_f32 v19, v38, v39
	v_cvt_pk_bf16_f32 v20, v40, v41
	v_cvt_pk_bf16_f32 v21, v42, v43
	v_cvt_pk_bf16_f32 v22, v44, v45
	v_cvt_pk_bf16_f32 v23, v46, v47
	v_cvt_pk_bf16_f32 v24, v48, v49
	v_cvt_pk_bf16_f32 v25, v50, v51
	v_cvt_pk_bf16_f32 v26, v52, v53
	v_cvt_pk_bf16_f32 v27, v54, v55
	v_cvt_pk_bf16_f32 v28, v56, v57
	v_cvt_pk_bf16_f32 v29, v58, v59
	v_cvt_pk_bf16_f32 v30, v60, v61
	v_cvt_pk_bf16_f32 v31, v62, v63
	global_store_dwordx4 v143, v[0:3], s[66:67]
	global_store_dwordx4 v143, v[4:7], s[66:67] offset:16
	global_store_dwordx4 v143, v[8:11], s[66:67] offset:32
	global_store_dwordx4 v143, v[12:15], s[66:67] offset:48
	global_store_dwordx4 v143, v[16:19], s[66:67] offset:64
	global_store_dwordx4 v143, v[20:23], s[66:67] offset:80
	global_store_dwordx4 v143, v[24:27], s[66:67] offset:96
	global_store_dwordx4 v143, v[28:31], s[66:67] offset:112
	s_branch .Llt1_next
; #define KIN(i) ((const float*)kptr<float>(i))
; __device__ __forceinline__ void transpose_item(const float* __restrict__ W, int ldw, bf16_t* __restrict__ WT, int ldo, const float* __restrict__ g, int k0, int n0, int dstrow, int lane) {
;     const float* src = W + (size_t)k0 * ldw + n0 + lane;
;     float v[64];
; #pragma unroll
;     for (int i = 0; i < 64; ++i) v[i] = __builtin_nontemporal_load(src + (size_t)i * ldw);
; __global__ void __launch_bounds__(NWAVES * 64, 2) fwd_mega(Args args) {
;     ...
;                 if (r < I_F1) { const int kb = r / 64, nb = r % 64; transpose_item(KIN(16) + (size_t)l * DM * DFF, DFF, (bf16_t*)(wl + W_FF1), DM, KIN(15) + l * DM, 64 * kb, 64 * nb, 64 * nb + lane, lane); continue; } r -= I_F1;
.Llt1_n1:
	s_cmpk_lt_u32 s63, 0x780
	s_cbranch_scc0 .Llt1_n2
	s_sub_u32 s4, s63, 0x380
	s_lshr_b32 s2, s4, 6
	s_and_b32 s3, s4, 63
	s_load_dwordx2 s[64:65], s[0:1], 0x80
	s_load_dwordx2 s[66:67], s[0:1], 0x98
	v_lshl_add_u32 v142, s3, 6, v191
	v_lshlrev_b32_e32 v143, 11, v142
	s_lshl_b32 s4, s2, 7
	v_add_u32_e32 v143, s4, v143
	v_lshlrev_b32_e32 v141, 2, v191
	s_waitcnt lgkmcnt(0)
	s_add_u32 s66, s66, 0x2400000
	s_addc_u32 s67, s67, 0
	s_mul_i32 s4, s2, 0x100000
	s_add_u32 s4, s4, 0x1000000
	s_add_u32 s64, s64, s4
	s_addc_u32 s65, s65, 0
	s_lshl_b32 s4, s3, 8
	s_add_u32 s64, s64, s4
	s_addc_u32 s65, s65, 0
	s_lshl_b32 s4, s2, 8
	s_load_dwordx2 s[2:3], s[0:1], 0x78
	global_load_dword v0, v141, s[64:65] nt
	s_add_u32 s64, s64, 0x4000
	s_addc_u32 s65, s65, 0
	global_load_dword v1, v141, s[64:65] nt
	s_add_u32 s64, s64, 0x4000
	s_addc_u32 s65, s65, 0
	global_load_dword v2, v141, s[64:65] nt
	s_add_u32 s64, s64, 0x4000
	s_addc_u32 s65, s65, 0
	global_load_dword v3, v141, s[64:65] nt
	s_add_u32 s64, s64, 0x4000
	s_addc_u32 s65, s65, 0
	global_load_dword v4, v141, s[64:65] nt
	s_add_u32 s64, s64, 0x4000
	s_addc_u32 s65, s65, 0
	global_load_dword v5, v141, s[64:65] nt
	s_add_u32 s64, s64, 0x4000
	s_addc_u32 s65, s65, 0
	global_load_dword v6, v141, s[64:65] nt
	s_add_u32 s64, s64, 0x4000
	s_addc_u32 s65, s65, 0
	global_load_dword v7, v141, s[64:65] nt
	s_add_u32 s64, s64, 0x4000
	s_addc_u32 s65, s65, 0
	global_load_dword v8, v141, s[64:65] nt
	s_add_u32 s64, s64, 0x4000
	s_addc_u32 s65, s65, 0
	global_load_dword v9, v141, s[64:65] nt
	s_add_u32 s64, s64, 0x4000
	s_addc_u32 s65, s65, 0
	global_load_dword v10, v141, s[64:65] nt
	s_add_u32 s64, s64, 0x4000
	s_addc_u32 s65, s65, 0
	global_load_dword v11, v141, s[64:65] nt
	s_add_u32 s64, s64, 0x4000
	s_addc_u32 s65, s65, 0
	global_load_dword v12, v141, s[64:65] nt
	s_add_u32 s64, s64, 0x4000
	s_addc_u32 s65, s65, 0
	global_load_dword v13, v141, s[64:65] nt
	s_add_u32 s64, s64, 0x4000
	s_addc_u32 s65, s65, 0
	global_load_dword v14, v141, s[64:65] nt
	s_add_u32 s64, s64, 0x4000
	s_addc_u32 s65, s65, 0
	global_load_dword v15, v141, s[64:65] nt
	s_add_u32 s64, s64, 0x4000
	s_addc_u32 s65, s65, 0
	global_load_dword v16, v141, s[64:65] nt
	s_add_u32 s64, s64, 0x4000
	s_addc_u32 s65, s65, 0
	global_load_dword v17, v141, s[64:65] nt
	s_add_u32 s64, s64, 0x4000
	s_addc_u32 s65, s65, 0
	global_load_dword v18, v141, s[64:65] nt
	s_add_u32 s64, s64, 0x4000
	s_addc_u32 s65, s65, 0
	global_load_dword v19, v141, s[64:65] nt
	s_add_u32 s64, s64, 0x4000
	s_addc_u32 s65, s65, 0
	global_load_dword v20, v141, s[64:65] nt
	s_add_u32 s64, s64, 0x4000
	s_addc_u32 s65, s65, 0
	global_load_dword v21, v141, s[64:65] nt
	s_add_u32 s64, s64, 0x4000
	s_addc_u32 s65, s65, 0
	global_load_dword v22, v141, s[64:65] nt
	s_add_u32 s64, s64, 0x4000
	s_addc_u32 s65, s65, 0
	global_load_dword v23, v141, s[64:65] nt
	s_add_u32 s64, s64, 0x4000
	s_addc_u32 s65, s65, 0
	global_load_dword v24, v141, s[64:65] nt
	s_add_u32 s64, s64, 0x4000
	s_addc_u32 s65, s65, 0
	global_load_dword v25, v141, s[64:65] nt
	s_add_u32 s64, s64, 0x4000
	s_addc_u32 s65, s65, 0
	global_load_dword v26, v141, s[64:65] nt
	s_add_u32 s64, s64, 0x4000
	s_addc_u32 s65, s65, 0
	global_load_dword v27, v141, s[64:65] nt
	s_add_u32 s64, s64, 0x4000
	s_addc_u32 s65, s65, 0
	global_load_dword v28, v141, s[64:65] nt
	s_add_u32 s64, s64, 0x4000
	s_addc_u32 s65, s65, 0
	global_load_dword v29, v141, s[64:65] nt
	s_add_u32 s64, s64, 0x4000
	s_addc_u32 s65, s65, 0
	global_load_dword v30, v141, s[64:65] nt
	s_add_u32 s64, s64, 0x4000
	s_addc_u32 s65, s65, 0
	global_load_dword v31, v141, s[64:65] nt
	s_add_u32 s64, s64, 0x4000
	s_addc_u32 s65, s65, 0
	global_load_dword v32, v141, s[64:65] nt
	s_add_u32 s64, s64, 0x4000
	s_addc_u32 s65, s65, 0
	global_load_dword v33, v141, s[64:65] nt
	s_add_u32 s64, s64, 0x4000
	s_addc_u32 s65, s65, 0
	global_load_dword v34, v141, s[64:65] nt
	s_add_u32 s64, s64, 0x4000
	s_addc_u32 s65, s65, 0
	global_load_dword v35, v141, s[64:65] nt
	s_add_u32 s64, s64, 0x4000
	s_addc_u32 s65, s65, 0
	global_load_dword v36, v141, s[64:65] nt
	s_add_u32 s64, s64, 0x4000
	s_addc_u32 s65, s65, 0
	global_load_dword v37, v141, s[64:65] nt
	s_add_u32 s64, s64, 0x4000
	s_addc_u32 s65, s65, 0
	global_load_dword v38, v141, s[64:65] nt
	s_add_u32 s64, s64, 0x4000
	s_addc_u32 s65, s65, 0
	global_load_dword v39, v141, s[64:65] nt
	s_add_u32 s64, s64, 0x4000
	s_addc_u32 s65, s65, 0
	global_load_dword v40, v141, s[64:65] nt
	s_add_u32 s64, s64, 0x4000
	s_addc_u32 s65, s65, 0
	global_load_dword v41, v141, s[64:65] nt
	s_add_u32 s64, s64, 0x4000
	s_addc_u32 s65, s65, 0
	global_load_dword v42, v141, s[64:65] nt
	s_add_u32 s64, s64, 0x4000
	s_addc_u32 s65, s65, 0
	global_load_dword v43, v141, s[64:65] nt
	s_add_u32 s64, s64, 0x4000
	s_addc_u32 s65, s65, 0
	global_load_dword v44, v141, s[64:65] nt
	s_add_u32 s64, s64, 0x4000
	s_addc_u32 s65, s65, 0
	global_load_dword v45, v141, s[64:65] nt
	s_add_u32 s64, s64, 0x4000
	s_addc_u32 s65, s65, 0
	global_load_dword v46, v141, s[64:65] nt
	s_add_u32 s64, s64, 0x4000
	s_addc_u32 s65, s65, 0
	global_load_dword v47, v141, s[64:65] nt
	s_add_u32 s64, s64, 0x4000
	s_addc_u32 s65, s65, 0
	global_load_dword v48, v141, s[64:65] nt
	s_add_u32 s64, s64, 0x4000
	s_addc_u32 s65, s65, 0
	global_load_dword v49, v141, s[64:65] nt
	s_add_u32 s64, s64, 0x4000
	s_addc_u32 s65, s65, 0
	global_load_dword v50, v141, s[64:65] nt
	s_add_u32 s64, s64, 0x4000
	s_addc_u32 s65, s65, 0
	global_load_dword v51, v141, s[64:65] nt
	s_add_u32 s64, s64, 0x4000
	s_addc_u32 s65, s65, 0
	global_load_dword v52, v141, s[64:65] nt
	s_add_u32 s64, s64, 0x4000
	s_addc_u32 s65, s65, 0
	global_load_dword v53, v141, s[64:65] nt
	s_add_u32 s64, s64, 0x4000
	s_addc_u32 s65, s65, 0
	global_load_dword v54, v141, s[64:65] nt
	s_add_u32 s64, s64, 0x4000
	s_addc_u32 s65, s65, 0
	global_load_dword v55, v141, s[64:65] nt
	s_add_u32 s64, s64, 0x4000
	s_addc_u32 s65, s65, 0
	global_load_dword v56, v141, s[64:65] nt
	s_add_u32 s64, s64, 0x4000
	s_addc_u32 s65, s65, 0
	global_load_dword v57, v141, s[64:65] nt
	s_add_u32 s64, s64, 0x4000
	s_addc_u32 s65, s65, 0
	global_load_dword v58, v141, s[64:65] nt
	s_add_u32 s64, s64, 0x4000
	s_addc_u32 s65, s65, 0
	global_load_dword v59, v141, s[64:65] nt
	s_add_u32 s64, s64, 0x4000
	s_addc_u32 s65, s65, 0
	global_load_dword v60, v141, s[64:65] nt
	s_add_u32 s64, s64, 0x4000
	s_addc_u32 s65, s65, 0
	global_load_dword v61, v141, s[64:65] nt
	s_add_u32 s64, s64, 0x4000
	s_addc_u32 s65, s65, 0
	global_load_dword v62, v141, s[64:65] nt
	s_add_u32 s64, s64, 0x4000
	s_addc_u32 s65, s65, 0
	global_load_dword v63, v141, s[64:65] nt
	s_waitcnt lgkmcnt(0)
; __device__ __forceinline__ unsigned pk2(float lo, float hi) { f32x2 v = {lo, hi}; bf16x2_t b = __builtin_convertvector(v, bf16x2_t); return __builtin_bit_cast(unsigned, b); }
; __device__ __forceinline__ void transpose_item(const float* __restrict__ W, int ldw, bf16_t* __restrict__ WT, int ldo, const float* __restrict__ g, int k0, int n0, int dstrow, int lane) {
;     ...
;     if (g) {
; #pragma unroll
;         for (int i = 0; i < 64; ++i) v[i] *= g[k0 + i];
;     }
;     bf16_t* dst = WT + (size_t)dstrow * ldo + k0;
; #pragma unroll
;     for (int c = 0; c < 8; ++c) { u32x4 o; o.x = pk2(v[8 * c], v[8 * c + 1]); o.y = pk2(v[8 * c + 2], v[8 * c + 3]); o.z = pk2(v[8 * c + 4], v[8 * c + 5]); o.w = pk2(v[8 * c + 6], v[8 * c + 7]);
;         *(u32x4*)(dst + 8 * c) = o; }
	s_add_u32 s4, s4, 0x1000
	s_add_u32 s2, s2, s4
	s_addc_u32 s3, s3, 0
	global_load_dword v64, v153, s[2:3]
	global_load_dword v65, v153, s[2:3] offset:4
	global_load_dword v66, v153, s[2:3] offset:8
	global_load_dword v67, v153, s[2:3] offset:12
	global_load_dword v68, v153, s[2:3] offset:16
	global_load_dword v69, v153, s[2:3] offset:20
	global_load_dword v70, v153, s[2:3] offset:24
	global_load_dword v71, v153, s[2:3] offset:28
	global_load_dword v72, v153, s[2:3] offset:32
	global_load_dword v73, v153, s[2:3] offset:36
	global_load_dword v74, v153, s[2:3] offset:40
	global_load_dword v75, v153, s[2:3] offset:44
	global_load_dword v76, v153, s[2:3] offset:48
	global_load_dword v77, v153, s[2:3] offset:52
	global_load_dword v78, v153, s[2:3] offset:56
	global_load_dword v79, v153, s[2:3] offset:60
	global_load_dword v80, v153, s[2:3] offset:64
	global_load_dword v81, v153, s[2:3] offset:68
	global_load_dword v82, v153, s[2:3] offset:72
	global_load_dword v83, v153, s[2:3] offset:76
	global_load_dword v84, v153, s[2:3] offset:80
	global_load_dword v85, v153, s[2:3] offset:84
	global_load_dword v86, v153, s[2:3] offset:88
	global_load_dword v87, v153, s[2:3] offset:92
	global_load_dword v88, v153, s[2:3] offset:96
	global_load_dword v89, v153, s[2:3] offset:100
	global_load_dword v90, v153, s[2:3] offset:104
	global_load_dword v91, v153, s[2:3] offset:108
	global_load_dword v92, v153, s[2:3] offset:112
	global_load_dword v93, v153, s[2:3] offset:116
	global_load_dword v94, v153, s[2:3] offset:120
	global_load_dword v95, v153, s[2:3] offset:124
	global_load_dword v96, v153, s[2:3] offset:128
	global_load_dword v97, v153, s[2:3] offset:132
	global_load_dword v98, v153, s[2:3] offset:136
	global_load_dword v99, v153, s[2:3] offset:140
	global_load_dword v100, v153, s[2:3] offset:144
	global_load_dword v101, v153, s[2:3] offset:148
	global_load_dword v102, v153, s[2:3] offset:152
	global_load_dword v103, v153, s[2:3] offset:156
	global_load_dword v104, v153, s[2:3] offset:160
	global_load_dword v105, v153, s[2:3] offset:164
	global_load_dword v106, v153, s[2:3] offset:168
	global_load_dword v107, v153, s[2:3] offset:172
	global_load_dword v108, v153, s[2:3] offset:176
	global_load_dword v109, v153, s[2:3] offset:180
	global_load_dword v110, v153, s[2:3] offset:184
	global_load_dword v111, v153, s[2:3] offset:188
	global_load_dword v112, v153, s[2:3] offset:192
	global_load_dword v113, v153, s[2:3] offset:196
	global_load_dword v114, v153, s[2:3] offset:200
	global_load_dword v115, v153, s[2:3] offset:204
	global_load_dword v116, v153, s[2:3] offset:208
	global_load_dword v117, v153, s[2:3] offset:212
	global_load_dword v118, v153, s[2:3] offset:216
	global_load_dword v119, v153, s[2:3] offset:220
	global_load_dword v120, v153, s[2:3] offset:224
	global_load_dword v121, v153, s[2:3] offset:228
	global_load_dword v122, v153, s[2:3] offset:232
	global_load_dword v123, v153, s[2:3] offset:236
	global_load_dword v124, v153, s[2:3] offset:240
	global_load_dword v125, v153, s[2:3] offset:244
	global_load_dword v126, v153, s[2:3] offset:248
	global_load_dword v127, v153, s[2:3] offset:252
	s_waitcnt vmcnt(0)
	v_mul_f32_e32 v0, v0, v64
	v_mul_f32_e32 v1, v1, v65
	v_mul_f32_e32 v2, v2, v66
	v_mul_f32_e32 v3, v3, v67
	v_mul_f32_e32 v4, v4, v68
	v_mul_f32_e32 v5, v5, v69
	v_mul_f32_e32 v6, v6, v70
	v_mul_f32_e32 v7, v7, v71
	v_mul_f32_e32 v8, v8, v72
	v_mul_f32_e32 v9, v9, v73
	v_mul_f32_e32 v10, v10, v74
	v_mul_f32_e32 v11, v11, v75
	v_mul_f32_e32 v12, v12, v76
	v_mul_f32_e32 v13, v13, v77
	v_mul_f32_e32 v14, v14, v78
	v_mul_f32_e32 v15, v15, v79
	v_mul_f32_e32 v16, v16, v80
	v_mul_f32_e32 v17, v17, v81
	v_mul_f32_e32 v18, v18, v82
	v_mul_f32_e32 v19, v19, v83
	v_mul_f32_e32 v20, v20, v84
	v_mul_f32_e32 v21, v21, v85
	v_mul_f32_e32 v22, v22, v86
	v_mul_f32_e32 v23, v23, v87
	v_mul_f32_e32 v24, v24, v88
	v_mul_f32_e32 v25, v25, v89
	v_mul_f32_e32 v26, v26, v90
	v_mul_f32_e32 v27, v27, v91
	v_mul_f32_e32 v28, v28, v92
	v_mul_f32_e32 v29, v29, v93
	v_mul_f32_e32 v30, v30, v94
	v_mul_f32_e32 v31, v31, v95
	v_mul_f32_e32 v32, v32, v96
	v_mul_f32_e32 v33, v33, v97
	v_mul_f32_e32 v34, v34, v98
	v_mul_f32_e32 v35, v35, v99
	v_mul_f32_e32 v36, v36, v100
	v_mul_f32_e32 v37, v37, v101
	v_mul_f32_e32 v38, v38, v102
	v_mul_f32_e32 v39, v39, v103
	v_mul_f32_e32 v40, v40, v104
	v_mul_f32_e32 v41, v41, v105
	v_mul_f32_e32 v42, v42, v106
	v_mul_f32_e32 v43, v43, v107
	v_mul_f32_e32 v44, v44, v108
	v_mul_f32_e32 v45, v45, v109
	v_mul_f32_e32 v46, v46, v110
	v_mul_f32_e32 v47, v47, v111
	v_mul_f32_e32 v48, v48, v112
	v_mul_f32_e32 v49, v49, v113
	v_mul_f32_e32 v50, v50, v114
	v_mul_f32_e32 v51, v51, v115
	v_mul_f32_e32 v52, v52, v116
	v_mul_f32_e32 v53, v53, v117
	v_mul_f32_e32 v54, v54, v118
	v_mul_f32_e32 v55, v55, v119
	v_mul_f32_e32 v56, v56, v120
	v_mul_f32_e32 v57, v57, v121
	v_mul_f32_e32 v58, v58, v122
	v_mul_f32_e32 v59, v59, v123
	v_mul_f32_e32 v60, v60, v124
	v_mul_f32_e32 v61, v61, v125
	v_mul_f32_e32 v62, v62, v126
	v_mul_f32_e32 v63, v63, v127
	v_cvt_pk_bf16_f32 v0, v0, v1
	v_cvt_pk_bf16_f32 v1, v2, v3
	v_cvt_pk_bf16_f32 v2, v4, v5
	v_cvt_pk_bf16_f32 v3, v6, v7
	v_cvt_pk_bf16_f32 v4, v8, v9
	v_cvt_pk_bf16_f32 v5, v10, v11
	v_cvt_pk_bf16_f32 v6, v12, v13
	v_cvt_pk_bf16_f32 v7, v14, v15
	v_cvt_pk_bf16_f32 v8, v16, v17
	v_cvt_pk_bf16_f32 v9, v18, v19
	v_cvt_pk_bf16_f32 v10, v20, v21
	v_cvt_pk_bf16_f32 v11, v22, v23
	v_cvt_pk_bf16_f32 v12, v24, v25
	v_cvt_pk_bf16_f32 v13, v26, v27
	v_cvt_pk_bf16_f32 v14, v28, v29
	v_cvt_pk_bf16_f32 v15, v30, v31
	v_cvt_pk_bf16_f32 v16, v32, v33
	v_cvt_pk_bf16_f32 v17, v34, v35
	v_cvt_pk_bf16_f32 v18, v36, v37
	v_cvt_pk_bf16_f32 v19, v38, v39
	v_cvt_pk_bf16_f32 v20, v40, v41
	v_cvt_pk_bf16_f32 v21, v42, v43
	v_cvt_pk_bf16_f32 v22, v44, v45
	v_cvt_pk_bf16_f32 v23, v46, v47
	v_cvt_pk_bf16_f32 v24, v48, v49
	v_cvt_pk_bf16_f32 v25, v50, v51
	v_cvt_pk_bf16_f32 v26, v52, v53
	v_cvt_pk_bf16_f32 v27, v54, v55
	v_cvt_pk_bf16_f32 v28, v56, v57
	v_cvt_pk_bf16_f32 v29, v58, v59
	v_cvt_pk_bf16_f32 v30, v60, v61
	v_cvt_pk_bf16_f32 v31, v62, v63
	global_store_dwordx4 v143, v[0:3], s[66:67]
	global_store_dwordx4 v143, v[4:7], s[66:67] offset:16
	global_store_dwordx4 v143, v[8:11], s[66:67] offset:32
	global_store_dwordx4 v143, v[12:15], s[66:67] offset:48
	global_store_dwordx4 v143, v[16:19], s[66:67] offset:64
	global_store_dwordx4 v143, v[20:23], s[66:67] offset:80
	global_store_dwordx4 v143, v[24:27], s[66:67] offset:96
	global_store_dwordx4 v143, v[28:31], s[66:67] offset:112
	s_branch .Llt1_next
; #define KIN(i) ((const float*)kptr<float>(i))
; __device__ __forceinline__ void transpose_item(const float* __restrict__ W, int ldw, bf16_t* __restrict__ WT, int ldo, const float* __restrict__ g, int k0, int n0, int dstrow, int lane) {
;     const float* src = W + (size_t)k0 * ldw + n0 + lane;
;     float v[64];
; #pragma unroll
;     for (int i = 0; i < 64; ++i) v[i] = __builtin_nontemporal_load(src + (size_t)i * ldw);
; __global__ void __launch_bounds__(NWAVES * 64, 2) fwd_mega(Args args) {
;     ...
;                 { const int kb = r / 16, nb = r % 16; transpose_item(KIN(17) + (size_t)l * DFF * DM, DM, (bf16_t*)(wl + W_FF2), DFF, nullptr, 64 * kb, 64 * nb, 64 * nb + lane, lane); }
.Llt1_n2:
	s_sub_u32 s4, s63, 0x780
	s_lshr_b32 s2, s4, 4
	s_and_b32 s3, s4, 15
	s_load_dwordx2 s[64:65], s[0:1], 0x88
	s_load_dwordx2 s[66:67], s[0:1], 0x98
	v_lshl_add_u32 v142, s3, 6, v191
	v_lshlrev_b32_e32 v143, 13, v142
	s_lshl_b32 s4, s2, 7
	v_add_u32_e32 v143, s4, v143
	v_lshlrev_b32_e32 v141, 2, v191
	s_waitcnt lgkmcnt(0)
	s_add_u32 s66, s66, 0x2c00000
	s_addc_u32 s67, s67, 0
	s_mul_i32 s4, s2, 0x40000
	s_add_u32 s4, s4, 0x1000000
	s_add_u32 s64, s64, s4
	s_addc_u32 s65, s65, 0
	s_lshl_b32 s4, s3, 8
	s_add_u32 s64, s64, s4
	s_addc_u32 s65, s65, 0
	global_load_dword v0, v141, s[64:65] nt
	s_add_u32 s64, s64, 0x1000
	s_addc_u32 s65, s65, 0
	global_load_dword v1, v141, s[64:65] nt
	s_add_u32 s64, s64, 0x1000
	s_addc_u32 s65, s65, 0
	global_load_dword v2, v141, s[64:65] nt
	s_add_u32 s64, s64, 0x1000
	s_addc_u32 s65, s65, 0
	global_load_dword v3, v141, s[64:65] nt
	s_add_u32 s64, s64, 0x1000
	s_addc_u32 s65, s65, 0
	global_load_dword v4, v141, s[64:65] nt
	s_add_u32 s64, s64, 0x1000
	s_addc_u32 s65, s65, 0
	global_load_dword v5, v141, s[64:65] nt
	s_add_u32 s64, s64, 0x1000
	s_addc_u32 s65, s65, 0
	global_load_dword v6, v141, s[64:65] nt
	s_add_u32 s64, s64, 0x1000
	s_addc_u32 s65, s65, 0
	global_load_dword v7, v141, s[64:65] nt
	s_add_u32 s64, s64, 0x1000
	s_addc_u32 s65, s65, 0
	global_load_dword v8, v141, s[64:65] nt
	s_add_u32 s64, s64, 0x1000
	s_addc_u32 s65, s65, 0
	global_load_dword v9, v141, s[64:65] nt
	s_add_u32 s64, s64, 0x1000
	s_addc_u32 s65, s65, 0
	global_load_dword v10, v141, s[64:65] nt
	s_add_u32 s64, s64, 0x1000
	s_addc_u32 s65, s65, 0
	global_load_dword v11, v141, s[64:65] nt
	s_add_u32 s64, s64, 0x1000
	s_addc_u32 s65, s65, 0
	global_load_dword v12, v141, s[64:65] nt
	s_add_u32 s64, s64, 0x1000
	s_addc_u32 s65, s65, 0
	global_load_dword v13, v141, s[64:65] nt
	s_add_u32 s64, s64, 0x1000
	s_addc_u32 s65, s65, 0
	global_load_dword v14, v141, s[64:65] nt
	s_add_u32 s64, s64, 0x1000
	s_addc_u32 s65, s65, 0
	global_load_dword v15, v141, s[64:65] nt
	s_add_u32 s64, s64, 0x1000
	s_addc_u32 s65, s65, 0
	global_load_dword v16, v141, s[64:65] nt
	s_add_u32 s64, s64, 0x1000
	s_addc_u32 s65, s65, 0
	global_load_dword v17, v141, s[64:65] nt
	s_add_u32 s64, s64, 0x1000
	s_addc_u32 s65, s65, 0
	global_load_dword v18, v141, s[64:65] nt
	s_add_u32 s64, s64, 0x1000
	s_addc_u32 s65, s65, 0
	global_load_dword v19, v141, s[64:65] nt
	s_add_u32 s64, s64, 0x1000
	s_addc_u32 s65, s65, 0
	global_load_dword v20, v141, s[64:65] nt
	s_add_u32 s64, s64, 0x1000
	s_addc_u32 s65, s65, 0
	global_load_dword v21, v141, s[64:65] nt
	s_add_u32 s64, s64, 0x1000
	s_addc_u32 s65, s65, 0
	global_load_dword v22, v141, s[64:65] nt
	s_add_u32 s64, s64, 0x1000
	s_addc_u32 s65, s65, 0
	global_load_dword v23, v141, s[64:65] nt
	s_add_u32 s64, s64, 0x1000
	s_addc_u32 s65, s65, 0
	global_load_dword v24, v141, s[64:65] nt
	s_add_u32 s64, s64, 0x1000
	s_addc_u32 s65, s65, 0
	global_load_dword v25, v141, s[64:65] nt
	s_add_u32 s64, s64, 0x1000
	s_addc_u32 s65, s65, 0
	global_load_dword v26, v141, s[64:65] nt
	s_add_u32 s64, s64, 0x1000
	s_addc_u32 s65, s65, 0
	global_load_dword v27, v141, s[64:65] nt
	s_add_u32 s64, s64, 0x1000
	s_addc_u32 s65, s65, 0
	global_load_dword v28, v141, s[64:65] nt
	s_add_u32 s64, s64, 0x1000
	s_addc_u32 s65, s65, 0
	global_load_dword v29, v141, s[64:65] nt
	s_add_u32 s64, s64, 0x1000
	s_addc_u32 s65, s65, 0
	global_load_dword v30, v141, s[64:65] nt
	s_add_u32 s64, s64, 0x1000
	s_addc_u32 s65, s65, 0
	global_load_dword v31, v141, s[64:65] nt
	s_add_u32 s64, s64, 0x1000
	s_addc_u32 s65, s65, 0
	global_load_dword v32, v141, s[64:65] nt
	s_add_u32 s64, s64, 0x1000
	s_addc_u32 s65, s65, 0
	global_load_dword v33, v141, s[64:65] nt
	s_add_u32 s64, s64, 0x1000
	s_addc_u32 s65, s65, 0
	global_load_dword v34, v141, s[64:65] nt
	s_add_u32 s64, s64, 0x1000
	s_addc_u32 s65, s65, 0
	global_load_dword v35, v141, s[64:65] nt
	s_add_u32 s64, s64, 0x1000
	s_addc_u32 s65, s65, 0
	global_load_dword v36, v141, s[64:65] nt
	s_add_u32 s64, s64, 0x1000
	s_addc_u32 s65, s65, 0
	global_load_dword v37, v141, s[64:65] nt
	s_add_u32 s64, s64, 0x1000
	s_addc_u32 s65, s65, 0
	global_load_dword v38, v141, s[64:65] nt
	s_add_u32 s64, s64, 0x1000
	s_addc_u32 s65, s65, 0
	global_load_dword v39, v141, s[64:65] nt
	s_add_u32 s64, s64, 0x1000
	s_addc_u32 s65, s65, 0
	global_load_dword v40, v141, s[64:65] nt
	s_add_u32 s64, s64, 0x1000
	s_addc_u32 s65, s65, 0
	global_load_dword v41, v141, s[64:65] nt
	s_add_u32 s64, s64, 0x1000
	s_addc_u32 s65, s65, 0
	global_load_dword v42, v141, s[64:65] nt
	s_add_u32 s64, s64, 0x1000
	s_addc_u32 s65, s65, 0
	global_load_dword v43, v141, s[64:65] nt
	s_add_u32 s64, s64, 0x1000
	s_addc_u32 s65, s65, 0
	global_load_dword v44, v141, s[64:65] nt
	s_add_u32 s64, s64, 0x1000
	s_addc_u32 s65, s65, 0
	global_load_dword v45, v141, s[64:65] nt
	s_add_u32 s64, s64, 0x1000
	s_addc_u32 s65, s65, 0
	global_load_dword v46, v141, s[64:65] nt
	s_add_u32 s64, s64, 0x1000
	s_addc_u32 s65, s65, 0
	global_load_dword v47, v141, s[64:65] nt
	s_add_u32 s64, s64, 0x1000
	s_addc_u32 s65, s65, 0
	global_load_dword v48, v141, s[64:65] nt
	s_add_u32 s64, s64, 0x1000
	s_addc_u32 s65, s65, 0
	global_load_dword v49, v141, s[64:65] nt
	s_add_u32 s64, s64, 0x1000
	s_addc_u32 s65, s65, 0
	global_load_dword v50, v141, s[64:65] nt
	s_add_u32 s64, s64, 0x1000
	s_addc_u32 s65, s65, 0
	global_load_dword v51, v141, s[64:65] nt
	s_add_u32 s64, s64, 0x1000
	s_addc_u32 s65, s65, 0
	global_load_dword v52, v141, s[64:65] nt
	s_add_u32 s64, s64, 0x1000
	s_addc_u32 s65, s65, 0
	global_load_dword v53, v141, s[64:65] nt
	s_add_u32 s64, s64, 0x1000
	s_addc_u32 s65, s65, 0
	global_load_dword v54, v141, s[64:65] nt
	s_add_u32 s64, s64, 0x1000
	s_addc_u32 s65, s65, 0
	global_load_dword v55, v141, s[64:65] nt
	s_add_u32 s64, s64, 0x1000
	s_addc_u32 s65, s65, 0
	global_load_dword v56, v141, s[64:65] nt
	s_add_u32 s64, s64, 0x1000
	s_addc_u32 s65, s65, 0
	global_load_dword v57, v141, s[64:65] nt
	s_add_u32 s64, s64, 0x1000
	s_addc_u32 s65, s65, 0
	global_load_dword v58, v141, s[64:65] nt
	s_add_u32 s64, s64, 0x1000
	s_addc_u32 s65, s65, 0
	global_load_dword v59, v141, s[64:65] nt
	s_add_u32 s64, s64, 0x1000
	s_addc_u32 s65, s65, 0
	global_load_dword v60, v141, s[64:65] nt
	s_add_u32 s64, s64, 0x1000
	s_addc_u32 s65, s65, 0
	global_load_dword v61, v141, s[64:65] nt
	s_add_u32 s64, s64, 0x1000
	s_addc_u32 s65, s65, 0
	global_load_dword v62, v141, s[64:65] nt
	s_add_u32 s64, s64, 0x1000
	s_addc_u32 s65, s65, 0
	global_load_dword v63, v141, s[64:65] nt
	s_waitcnt vmcnt(0)
; __device__ __forceinline__ unsigned pk2(float lo, float hi) { f32x2 v = {lo, hi}; bf16x2_t b = __builtin_convertvector(v, bf16x2_t); return __builtin_bit_cast(unsigned, b); }
; __device__ __forceinline__ void transpose_item(const float* __restrict__ W, int ldw, bf16_t* __restrict__ WT, int ldo, const float* __restrict__ g, int k0, int n0, int dstrow, int lane) {
;     ...
;     for (int c = 0; c < 8; ++c) { u32x4 o; o.x = pk2(v[8 * c], v[8 * c + 1]); o.y = pk2(v[8 * c + 2], v[8 * c + 3]); o.z = pk2(v[8 * c + 4], v[8 * c + 5]); o.w = pk2(v[8 * c + 6], v[8 * c + 7]);
;         *(u32x4*)(dst + 8 * c) = o; }
	v_cvt_pk_bf16_f32 v0, v0, v1
	v_cvt_pk_bf16_f32 v1, v2, v3
	v_cvt_pk_bf16_f32 v2, v4, v5
	v_cvt_pk_bf16_f32 v3, v6, v7
	v_cvt_pk_bf16_f32 v4, v8, v9
	v_cvt_pk_bf16_f32 v5, v10, v11
	v_cvt_pk_bf16_f32 v6, v12, v13
	v_cvt_pk_bf16_f32 v7, v14, v15
	v_cvt_pk_bf16_f32 v8, v16, v17
	v_cvt_pk_bf16_f32 v9, v18, v19
	v_cvt_pk_bf16_f32 v10, v20, v21
	v_cvt_pk_bf16_f32 v11, v22, v23
	v_cvt_pk_bf16_f32 v12, v24, v25
	v_cvt_pk_bf16_f32 v13, v26, v27
	v_cvt_pk_bf16_f32 v14, v28, v29
	v_cvt_pk_bf16_f32 v15, v30, v31
	v_cvt_pk_bf16_f32 v16, v32, v33
	v_cvt_pk_bf16_f32 v17, v34, v35
	v_cvt_pk_bf16_f32 v18, v36, v37
	v_cvt_pk_bf16_f32 v19, v38, v39
	v_cvt_pk_bf16_f32 v20, v40, v41
	v_cvt_pk_bf16_f32 v21, v42, v43
	v_cvt_pk_bf16_f32 v22, v44, v45
	v_cvt_pk_bf16_f32 v23, v46, v47
	v_cvt_pk_bf16_f32 v24, v48, v49
	v_cvt_pk_bf16_f32 v25, v50, v51
	v_cvt_pk_bf16_f32 v26, v52, v53
	v_cvt_pk_bf16_f32 v27, v54, v55
	v_cvt_pk_bf16_f32 v28, v56, v57
	v_cvt_pk_bf16_f32 v29, v58, v59
	v_cvt_pk_bf16_f32 v30, v60, v61
	v_cvt_pk_bf16_f32 v31, v62, v63
	global_store_dwordx4 v143, v[0:3], s[66:67]
	global_store_dwordx4 v143, v[4:7], s[66:67] offset:16
	global_store_dwordx4 v143, v[8:11], s[66:67] offset:32
	global_store_dwordx4 v143, v[12:15], s[66:67] offset:48
	global_store_dwordx4 v143, v[16:19], s[66:67] offset:64
	global_store_dwordx4 v143, v[20:23], s[66:67] offset:80
	global_store_dwordx4 v143, v[24:27], s[66:67] offset:96
	global_store_dwordx4 v143, v[28:31], s[66:67] offset:112
